# conv: row prefetch depth 8 instead of 4 (16 loads in flight per wave)
# speedup vs baseline: 1.0032x; 1.0028x over previous
; __device__ __forceinline__ unsigned cvt_pk_bf16(float lo, float hi) { unsigned r; asm volatile("v_cvt_pk_bf16_f32 %0, %1, %2" : "=v"(r) : "v"(lo), "v"(hi)); return r; }
; __device__ __forceinline__ float bf_lo(unsigned w) { return __uint_as_float(w << 16); }
; __device__ __forceinline__ float bf_hi(unsigned w) { return __uint_as_float(w & 0xffff0000u); }
; __global__ void __launch_bounds__(512, 2) trunk_fwd(Args args) {
;     ...
;                 u32x4 gb_n = *(const u32x4*)(Z + (size_t)r0 * INP + 768 + c0), gu_n = *(const u32x4*)(Z + (size_t)r0 * INP + 1280 + c0);
;                 f32x4 pv_n = *(const f32x4*)(pl + (size_t)r0 * PLE + lane * 4);
; #pragma nounroll
;                 for (int rr = 0; rr < 16; ++rr) {
;                     const int r = r0 + rr;
;                     const u32x4 gb = gb_n, gu = gu_n; const f32x4 pv4 = pv_n;
;                     if (rr < 15) { gb_n = *(const u32x4*)(Z + (size_t)(r + 1) * INP + 768 + c0); gu_n = *(const u32x4*)(Z + (size_t)(r + 1) * INP + 1280 + c0);
;                                    pv_n = *(const f32x4*)(pl + (size_t)(r + 1) * PLE + lane * 4); }
;                     float cv[8], uu[8]; float ss = 0.f;
; #pragma unroll
;                     for (int i = 0; i < 4; ++i) {
;                         uu[2 * i] = bf_lo(gu[i]); uu[2 * i + 1] = bf_hi(gu[i]);
;                         cv[2 * i] = bf_lo(gb[i]) * (w0[2 * i] * uu[2 * i] + w1[2 * i] * u1[2 * i] + w2[2 * i] * u2[2 * i]);
;                         cv[2 * i + 1] = bf_hi(gb[i]) * (w0[2 * i + 1] * uu[2 * i + 1] + w1[2 * i + 1] * u1[2 * i + 1] + w2[2 * i + 1] * u2[2 * i + 1]);
;                     }
; #pragma unroll
;                     for (int i = 0; i < 8; ++i) { ss += cv[i] * cv[i]; u2[i] = u1[i]; u1[i] = uu[i]; }
;                     ss = wave_sum(ss);
;                     const float rc = rsqrtf(ss * (1.0f / 512.0f) + EPS);
;                     u32x4 oc;
; #pragma unroll
;                     for (int i = 0; i < 4; ++i) oc[i] = cvt_pk_bf16(cv[2 * i] * rc, cv[2 * i + 1] * rc);
;                     *(u32x4*)(MIX + (size_t)r * 1024 + 512 + c0) = oc;
.Lcv_taps_ok:
	v_mad_i64_i32 v[152:153], vcc, s41, v221, v[58:59]
	s_add_u32 s41, s41, 1
	global_load_dwordx4 v[2:5], v[152:153], off offset:1536
	global_load_dwordx4 v[18:21], v[152:153], off offset:2560
	v_mad_i64_i32 v[152:153], vcc, s41, v221, v[58:59]
	s_add_u32 s41, s41, 1
	global_load_dwordx4 v[6:9], v[152:153], off offset:1536
	global_load_dwordx4 v[22:25], v[152:153], off offset:2560
	v_mad_i64_i32 v[152:153], vcc, s41, v221, v[58:59]
	s_add_u32 s41, s41, 1
	global_load_dwordx4 v[10:13], v[152:153], off offset:1536
	global_load_dwordx4 v[26:29], v[152:153], off offset:2560
	v_mad_i64_i32 v[152:153], vcc, s41, v221, v[58:59]
	s_add_u32 s41, s41, 1
	global_load_dwordx4 v[14:17], v[152:153], off offset:1536
	global_load_dwordx4 v[30:33], v[152:153], off offset:2560
	v_mad_i64_i32 v[152:153], vcc, s41, v221, v[58:59]
	s_add_u32 s41, s41, 1
	global_load_dwordx4 v[34:37], v[152:153], off offset:1536
	global_load_dwordx4 v[60:63], v[152:153], off offset:2560
	v_mad_i64_i32 v[152:153], vcc, s41, v221, v[58:59]
	s_add_u32 s41, s41, 1
	global_load_dwordx4 v[38:41], v[152:153], off offset:1536
	global_load_dwordx4 v[64:67], v[152:153], off offset:2560
	v_mad_i64_i32 v[152:153], vcc, s41, v221, v[58:59]
	s_add_u32 s41, s41, 1
	global_load_dwordx4 v[42:45], v[152:153], off offset:1536
	global_load_dwordx4 v[68:71], v[152:153], off offset:2560
	v_mad_i64_i32 v[152:153], vcc, s41, v221, v[58:59]
	s_add_u32 s41, s41, 1
	global_load_dwordx4 v[46:49], v[152:153], off offset:1536
	global_load_dwordx4 v[72:75], v[152:153], off offset:2560
	s_waitcnt vmcnt(14)
	v_lshlrev_b32_e32 v188, 16, v18
	v_and_b32_e32 v189, 0xffff0000, v18
	v_lshlrev_b32_e32 v190, 16, v19
	v_and_b32_e32 v191, 0xffff0000, v19
	v_lshlrev_b32_e32 v192, 16, v20
	v_and_b32_e32 v193, 0xffff0000, v20
	v_lshlrev_b32_e32 v194, 16, v21
	v_and_b32_e32 v195, 0xffff0000, v21
	v_mul_f32_e32 v140, v164, v188
	v_mul_f32_e32 v141, v165, v189
	v_mul_f32_e32 v142, v166, v190
	v_mul_f32_e32 v143, v167, v191
	v_mul_f32_e32 v144, v168, v192
	v_mul_f32_e32 v145, v169, v193
	v_mul_f32_e32 v146, v170, v194
	v_mul_f32_e32 v147, v171, v195
	v_fmac_f32_e32 v140, v172, v204
	v_fmac_f32_e32 v141, v173, v205
	v_fmac_f32_e32 v142, v174, v206
	v_fmac_f32_e32 v143, v175, v207
	v_fmac_f32_e32 v144, v176, v208
	v_fmac_f32_e32 v145, v177, v209
	v_fmac_f32_e32 v146, v178, v210
	v_fmac_f32_e32 v147, v179, v211
	v_fmac_f32_e32 v140, v180, v196
	v_fmac_f32_e32 v141, v181, v197
	v_fmac_f32_e32 v142, v182, v198
	v_fmac_f32_e32 v143, v183, v199
	v_fmac_f32_e32 v144, v184, v200
	v_fmac_f32_e32 v145, v185, v201
	v_fmac_f32_e32 v146, v186, v202
	v_fmac_f32_e32 v147, v187, v203
	v_lshlrev_b32_e32 v150, 16, v2
	v_and_b32_e32 v151, 0xffff0000, v2
	v_mul_f32_e32 v140, v150, v140
	v_mul_f32_e32 v141, v151, v141
	v_lshlrev_b32_e32 v150, 16, v3
	v_and_b32_e32 v151, 0xffff0000, v3
	v_mul_f32_e32 v142, v150, v142
	v_mul_f32_e32 v143, v151, v143
	v_lshlrev_b32_e32 v150, 16, v4
	v_and_b32_e32 v151, 0xffff0000, v4
	v_mul_f32_e32 v144, v150, v144
	v_mul_f32_e32 v145, v151, v145
	v_lshlrev_b32_e32 v150, 16, v5
	v_and_b32_e32 v151, 0xffff0000, v5
	v_mul_f32_e32 v146, v150, v146
	v_mul_f32_e32 v147, v151, v147
	v_mul_f32_e32 v148, v140, v140
	v_fmac_f32_e32 v148, v141, v141
	v_fmac_f32_e32 v148, v142, v142
	v_fmac_f32_e32 v148, v143, v143
	v_fmac_f32_e32 v148, v144, v144
	v_fmac_f32_e32 v148, v145, v145
	v_fmac_f32_e32 v148, v146, v146
	v_fmac_f32_e32 v148, v147, v147
	v_mad_i64_i32 v[152:153], vcc, s41, v221, v[58:59]
	s_add_u32 s41, s41, 1
	global_load_dwordx4 v[2:5], v[152:153], off offset:1536
	global_load_dwordx4 v[18:21], v[152:153], off offset:2560
	s_nop 1
	v_add_f32_dpp v148, v148, v148 quad_perm:[1,0,3,2] row_mask:0xf bank_mask:0xf
	s_nop 1
	v_add_f32_dpp v148, v148, v148 quad_perm:[2,3,0,1] row_mask:0xf bank_mask:0xf
	s_nop 1
	v_add_f32_dpp v148, v148, v148 row_half_mirror row_mask:0xf bank_mask:0xf
	s_nop 1
	v_add_f32_dpp v148, v148, v148 row_mirror row_mask:0xf bank_mask:0xf
	s_nop 1
	v_add_f32_dpp v148, v148, v148 row_bcast:15 row_mask:0xa bank_mask:0xf
	s_nop 1
	v_add_f32_dpp v148, v148, v148 row_bcast:31 row_mask:0xc bank_mask:0xf
	s_nop 0
	v_readlane_b32 s0, v148, 63
	s_nop 1
	v_mov_b32_e32 v148, s0
	v_fmamk_f32 v148, v148, 0x3b000000, v162
	v_mul_f32_e32 v150, 0x4b800000, v148
	v_cmp_gt_f32_e32 vcc, s31, v148
	s_nop 1
	v_cndmask_b32_e32 v148, v148, v150, vcc
	v_rsq_f32_e32 v148, v148
	s_nop 0
	v_mul_f32_e32 v150, 0x45800000, v148
	v_cndmask_b32_e32 v149, v148, v150, vcc
	v_mul_f32_e32 v140, v149, v140
	v_mul_f32_e32 v141, v149, v141
	v_mul_f32_e32 v142, v149, v142
	v_mul_f32_e32 v143, v149, v143
	v_mul_f32_e32 v144, v149, v144
	v_mul_f32_e32 v145, v149, v145
	v_mul_f32_e32 v146, v149, v146
	v_mul_f32_e32 v147, v149, v147
	v_cvt_pk_bf16_f32 v140, v140, v141
	v_cvt_pk_bf16_f32 v141, v142, v143
	v_cvt_pk_bf16_f32 v142, v144, v145
	v_cvt_pk_bf16_f32 v143, v146, v147
	global_store_dwordx4 v[156:157], v[140:143], off sc1
	s_waitcnt vmcnt(15)
; __device__ __forceinline__ unsigned cvt_pk_bf16(float lo, float hi) { unsigned r; asm volatile("v_cvt_pk_bf16_f32 %0, %1, %2" : "=v"(r) : "v"(lo), "v"(hi)); return r; }
; __device__ __forceinline__ float bf_lo(unsigned w) { return __uint_as_float(w << 16); }
; __device__ __forceinline__ float bf_hi(unsigned w) { return __uint_as_float(w & 0xffff0000u); }
; __global__ void __launch_bounds__(512, 2) trunk_fwd(Args args) {
;     ...
;                 for (int rr = 0; rr < 16; ++rr) {
;                     const int r = r0 + rr;
;                     const u32x4 gb = gb_n, gu = gu_n; const f32x4 pv4 = pv_n;
;                     if (rr < 15) { gb_n = *(const u32x4*)(Z + (size_t)(r + 1) * INP + 768 + c0); gu_n = *(const u32x4*)(Z + (size_t)(r + 1) * INP + 1280 + c0);
;                                    pv_n = *(const f32x4*)(pl + (size_t)(r + 1) * PLE + lane * 4); }
;                     float cv[8], uu[8]; float ss = 0.f;
; #pragma unroll
;                     for (int i = 0; i < 4; ++i) {
;                         uu[2 * i] = bf_lo(gu[i]); uu[2 * i + 1] = bf_hi(gu[i]);
;                         cv[2 * i] = bf_lo(gb[i]) * (w0[2 * i] * uu[2 * i] + w1[2 * i] * u1[2 * i] + w2[2 * i] * u2[2 * i]);
;                         cv[2 * i + 1] = bf_hi(gb[i]) * (w0[2 * i + 1] * uu[2 * i + 1] + w1[2 * i + 1] * u1[2 * i + 1] + w2[2 * i + 1] * u2[2 * i + 1]);
;                     }
; #pragma unroll
;                     for (int i = 0; i < 8; ++i) { ss += cv[i] * cv[i]; u2[i] = u1[i]; u1[i] = uu[i]; }
;                     ss = wave_sum(ss);
;                     const float rc = rsqrtf(ss * (1.0f / 512.0f) + EPS);
;                     u32x4 oc;
; #pragma unroll
;                     for (int i = 0; i < 4; ++i) oc[i] = cvt_pk_bf16(cv[2 * i] * rc, cv[2 * i + 1] * rc);
;                     *(u32x4*)(MIX + (size_t)r * 1024 + 512 + c0) = oc;
	v_lshlrev_b32_e32 v196, 16, v22
	v_and_b32_e32 v197, 0xffff0000, v22
	v_lshlrev_b32_e32 v198, 16, v23
	v_and_b32_e32 v199, 0xffff0000, v23
	v_lshlrev_b32_e32 v200, 16, v24
	v_and_b32_e32 v201, 0xffff0000, v24
	v_lshlrev_b32_e32 v202, 16, v25
	v_and_b32_e32 v203, 0xffff0000, v25
	v_mul_f32_e32 v140, v164, v196
	v_mul_f32_e32 v141, v165, v197
	v_mul_f32_e32 v142, v166, v198
	v_mul_f32_e32 v143, v167, v199
	v_mul_f32_e32 v144, v168, v200
	v_mul_f32_e32 v145, v169, v201
	v_mul_f32_e32 v146, v170, v202
	v_mul_f32_e32 v147, v171, v203
	v_fmac_f32_e32 v140, v172, v188
	v_fmac_f32_e32 v141, v173, v189
	v_fmac_f32_e32 v142, v174, v190
	v_fmac_f32_e32 v143, v175, v191
	v_fmac_f32_e32 v144, v176, v192
	v_fmac_f32_e32 v145, v177, v193
	v_fmac_f32_e32 v146, v178, v194
	v_fmac_f32_e32 v147, v179, v195
	v_fmac_f32_e32 v140, v180, v204
	v_fmac_f32_e32 v141, v181, v205
	v_fmac_f32_e32 v142, v182, v206
	v_fmac_f32_e32 v143, v183, v207
	v_fmac_f32_e32 v144, v184, v208
	v_fmac_f32_e32 v145, v185, v209
	v_fmac_f32_e32 v146, v186, v210
	v_fmac_f32_e32 v147, v187, v211
	v_lshlrev_b32_e32 v150, 16, v6
	v_and_b32_e32 v151, 0xffff0000, v6
	v_mul_f32_e32 v140, v150, v140
	v_mul_f32_e32 v141, v151, v141
	v_lshlrev_b32_e32 v150, 16, v7
	v_and_b32_e32 v151, 0xffff0000, v7
	v_mul_f32_e32 v142, v150, v142
	v_mul_f32_e32 v143, v151, v143
	v_lshlrev_b32_e32 v150, 16, v8
	v_and_b32_e32 v151, 0xffff0000, v8
	v_mul_f32_e32 v144, v150, v144
	v_mul_f32_e32 v145, v151, v145
	v_lshlrev_b32_e32 v150, 16, v9
	v_and_b32_e32 v151, 0xffff0000, v9
	v_mul_f32_e32 v146, v150, v146
	v_mul_f32_e32 v147, v151, v147
	v_mul_f32_e32 v148, v140, v140
	v_fmac_f32_e32 v148, v141, v141
	v_fmac_f32_e32 v148, v142, v142
	v_fmac_f32_e32 v148, v143, v143
	v_fmac_f32_e32 v148, v144, v144
	v_fmac_f32_e32 v148, v145, v145
	v_fmac_f32_e32 v148, v146, v146
	v_fmac_f32_e32 v148, v147, v147
	v_mad_i64_i32 v[152:153], vcc, s41, v221, v[58:59]
	s_add_u32 s41, s41, 1
	global_load_dwordx4 v[6:9], v[152:153], off offset:1536
	global_load_dwordx4 v[22:25], v[152:153], off offset:2560
	s_nop 1
	v_add_f32_dpp v148, v148, v148 quad_perm:[1,0,3,2] row_mask:0xf bank_mask:0xf
	s_nop 1
	v_add_f32_dpp v148, v148, v148 quad_perm:[2,3,0,1] row_mask:0xf bank_mask:0xf
	s_nop 1
	v_add_f32_dpp v148, v148, v148 row_half_mirror row_mask:0xf bank_mask:0xf
	s_nop 1
	v_add_f32_dpp v148, v148, v148 row_mirror row_mask:0xf bank_mask:0xf
	s_nop 1
	v_add_f32_dpp v148, v148, v148 row_bcast:15 row_mask:0xa bank_mask:0xf
	s_nop 1
	v_add_f32_dpp v148, v148, v148 row_bcast:31 row_mask:0xc bank_mask:0xf
	s_nop 0
	v_readlane_b32 s0, v148, 63
	s_nop 1
	v_mov_b32_e32 v148, s0
	v_fmamk_f32 v148, v148, 0x3b000000, v162
	v_mul_f32_e32 v150, 0x4b800000, v148
	v_cmp_gt_f32_e32 vcc, s31, v148
	s_nop 1
	v_cndmask_b32_e32 v148, v148, v150, vcc
	v_rsq_f32_e32 v148, v148
	s_nop 0
	v_mul_f32_e32 v150, 0x45800000, v148
	v_cndmask_b32_e32 v149, v148, v150, vcc
	v_mul_f32_e32 v140, v149, v140
	v_mul_f32_e32 v141, v149, v141
	v_mul_f32_e32 v142, v149, v142
	v_mul_f32_e32 v143, v149, v143
	v_mul_f32_e32 v144, v149, v144
	v_mul_f32_e32 v145, v149, v145
	v_mul_f32_e32 v146, v149, v146
	v_mul_f32_e32 v147, v149, v147
	v_cvt_pk_bf16_f32 v140, v140, v141
	v_cvt_pk_bf16_f32 v141, v142, v143
	v_cvt_pk_bf16_f32 v142, v144, v145
	v_cvt_pk_bf16_f32 v143, v146, v147
	global_store_dwordx4 v[156:157], v[140:143], off offset:2048 sc1
	v_lshl_add_u64 v[156:157], v[156:157], 0, s[20:21]
	s_waitcnt vmcnt(16)
	v_lshlrev_b32_e32 v204, 16, v26
	v_and_b32_e32 v205, 0xffff0000, v26
	v_lshlrev_b32_e32 v206, 16, v27
	v_and_b32_e32 v207, 0xffff0000, v27
	v_lshlrev_b32_e32 v208, 16, v28
	v_and_b32_e32 v209, 0xffff0000, v28
	v_lshlrev_b32_e32 v210, 16, v29
	v_and_b32_e32 v211, 0xffff0000, v29
	v_mul_f32_e32 v140, v164, v204
	v_mul_f32_e32 v141, v165, v205
	v_mul_f32_e32 v142, v166, v206
	v_mul_f32_e32 v143, v167, v207
	v_mul_f32_e32 v144, v168, v208
	v_mul_f32_e32 v145, v169, v209
	v_mul_f32_e32 v146, v170, v210
	v_mul_f32_e32 v147, v171, v211
	v_fmac_f32_e32 v140, v172, v196
	v_fmac_f32_e32 v141, v173, v197
	v_fmac_f32_e32 v142, v174, v198
	v_fmac_f32_e32 v143, v175, v199
	v_fmac_f32_e32 v144, v176, v200
	v_fmac_f32_e32 v145, v177, v201
	v_fmac_f32_e32 v146, v178, v202
	v_fmac_f32_e32 v147, v179, v203
	v_fmac_f32_e32 v140, v180, v188
	v_fmac_f32_e32 v141, v181, v189
	v_fmac_f32_e32 v142, v182, v190
	v_fmac_f32_e32 v143, v183, v191
	v_fmac_f32_e32 v144, v184, v192
	v_fmac_f32_e32 v145, v185, v193
	v_fmac_f32_e32 v146, v186, v194
	v_fmac_f32_e32 v147, v187, v195
	v_lshlrev_b32_e32 v150, 16, v10
	v_and_b32_e32 v151, 0xffff0000, v10
	v_mul_f32_e32 v140, v150, v140
	v_mul_f32_e32 v141, v151, v141
	v_lshlrev_b32_e32 v150, 16, v11
	v_and_b32_e32 v151, 0xffff0000, v11
	v_mul_f32_e32 v142, v150, v142
	v_mul_f32_e32 v143, v151, v143
	v_lshlrev_b32_e32 v150, 16, v12
	v_and_b32_e32 v151, 0xffff0000, v12
	v_mul_f32_e32 v144, v150, v144
	v_mul_f32_e32 v145, v151, v145
	v_lshlrev_b32_e32 v150, 16, v13
	v_and_b32_e32 v151, 0xffff0000, v13
	v_mul_f32_e32 v146, v150, v146
	v_mul_f32_e32 v147, v151, v147
	v_mul_f32_e32 v148, v140, v140
	v_fmac_f32_e32 v148, v141, v141
	v_fmac_f32_e32 v148, v142, v142
	v_fmac_f32_e32 v148, v143, v143
	v_fmac_f32_e32 v148, v144, v144
	v_fmac_f32_e32 v148, v145, v145
	v_fmac_f32_e32 v148, v146, v146
	v_fmac_f32_e32 v148, v147, v147
	v_mad_i64_i32 v[152:153], vcc, s41, v221, v[58:59]
	s_add_u32 s41, s41, 1
	global_load_dwordx4 v[10:13], v[152:153], off offset:1536
	global_load_dwordx4 v[26:29], v[152:153], off offset:2560
	s_nop 1
	v_add_f32_dpp v148, v148, v148 quad_perm:[1,0,3,2] row_mask:0xf bank_mask:0xf
	s_nop 1
	v_add_f32_dpp v148, v148, v148 quad_perm:[2,3,0,1] row_mask:0xf bank_mask:0xf
	s_nop 1
	v_add_f32_dpp v148, v148, v148 row_half_mirror row_mask:0xf bank_mask:0xf
	s_nop 1
	v_add_f32_dpp v148, v148, v148 row_mirror row_mask:0xf bank_mask:0xf
	s_nop 1
	v_add_f32_dpp v148, v148, v148 row_bcast:15 row_mask:0xa bank_mask:0xf
	s_nop 1
	v_add_f32_dpp v148, v148, v148 row_bcast:31 row_mask:0xc bank_mask:0xf
	s_nop 0
	v_readlane_b32 s0, v148, 63
	s_nop 1
	v_mov_b32_e32 v148, s0
	v_fmamk_f32 v148, v148, 0x3b000000, v162
	v_mul_f32_e32 v150, 0x4b800000, v148
	v_cmp_gt_f32_e32 vcc, s31, v148
	s_nop 1
	v_cndmask_b32_e32 v148, v148, v150, vcc
	v_rsq_f32_e32 v148, v148
	s_nop 0
	v_mul_f32_e32 v150, 0x45800000, v148
	v_cndmask_b32_e32 v149, v148, v150, vcc
	v_mul_f32_e32 v140, v149, v140
	v_mul_f32_e32 v141, v149, v141
	v_mul_f32_e32 v142, v149, v142
	v_mul_f32_e32 v143, v149, v143
	v_mul_f32_e32 v144, v149, v144
	v_mul_f32_e32 v145, v149, v145
	v_mul_f32_e32 v146, v149, v146
	v_mul_f32_e32 v147, v149, v147
	v_cvt_pk_bf16_f32 v140, v140, v141
	v_cvt_pk_bf16_f32 v141, v142, v143
	v_cvt_pk_bf16_f32 v142, v144, v145
	v_cvt_pk_bf16_f32 v143, v146, v147
	global_store_dwordx4 v[156:157], v[140:143], off sc1
	s_waitcnt vmcnt(17)
; __device__ __forceinline__ unsigned cvt_pk_bf16(float lo, float hi) { unsigned r; asm volatile("v_cvt_pk_bf16_f32 %0, %1, %2" : "=v"(r) : "v"(lo), "v"(hi)); return r; }
; __device__ __forceinline__ float bf_lo(unsigned w) { return __uint_as_float(w << 16); }
; __device__ __forceinline__ float bf_hi(unsigned w) { return __uint_as_float(w & 0xffff0000u); }
; __global__ void __launch_bounds__(512, 2) trunk_fwd(Args args) {
;     ...
;                 for (int rr = 0; rr < 16; ++rr) {
;                     const int r = r0 + rr;
;                     const u32x4 gb = gb_n, gu = gu_n; const f32x4 pv4 = pv_n;
;                     if (rr < 15) { gb_n = *(const u32x4*)(Z + (size_t)(r + 1) * INP + 768 + c0); gu_n = *(const u32x4*)(Z + (size_t)(r + 1) * INP + 1280 + c0);
;                                    pv_n = *(const f32x4*)(pl + (size_t)(r + 1) * PLE + lane * 4); }
;                     float cv[8], uu[8]; float ss = 0.f;
; #pragma unroll
;                     for (int i = 0; i < 4; ++i) {
;                         uu[2 * i] = bf_lo(gu[i]); uu[2 * i + 1] = bf_hi(gu[i]);
;                         cv[2 * i] = bf_lo(gb[i]) * (w0[2 * i] * uu[2 * i] + w1[2 * i] * u1[2 * i] + w2[2 * i] * u2[2 * i]);
;                         cv[2 * i + 1] = bf_hi(gb[i]) * (w0[2 * i + 1] * uu[2 * i + 1] + w1[2 * i + 1] * u1[2 * i + 1] + w2[2 * i + 1] * u2[2 * i + 1]);
;                     }
; #pragma unroll
;                     for (int i = 0; i < 8; ++i) { ss += cv[i] * cv[i]; u2[i] = u1[i]; u1[i] = uu[i]; }
;                     ss = wave_sum(ss);
;                     const float rc = rsqrtf(ss * (1.0f / 512.0f) + EPS);
;                     u32x4 oc;
; #pragma unroll
;                     for (int i = 0; i < 4; ++i) oc[i] = cvt_pk_bf16(cv[2 * i] * rc, cv[2 * i + 1] * rc);
;                     *(u32x4*)(MIX + (size_t)r * 1024 + 512 + c0) = oc;
	v_lshlrev_b32_e32 v188, 16, v30
	v_and_b32_e32 v189, 0xffff0000, v30
	v_lshlrev_b32_e32 v190, 16, v31
	v_and_b32_e32 v191, 0xffff0000, v31
	v_lshlrev_b32_e32 v192, 16, v32
	v_and_b32_e32 v193, 0xffff0000, v32
	v_lshlrev_b32_e32 v194, 16, v33
	v_and_b32_e32 v195, 0xffff0000, v33
	v_mul_f32_e32 v140, v164, v188
	v_mul_f32_e32 v141, v165, v189
	v_mul_f32_e32 v142, v166, v190
	v_mul_f32_e32 v143, v167, v191
	v_mul_f32_e32 v144, v168, v192
	v_mul_f32_e32 v145, v169, v193
	v_mul_f32_e32 v146, v170, v194
	v_mul_f32_e32 v147, v171, v195
	v_fmac_f32_e32 v140, v172, v204
	v_fmac_f32_e32 v141, v173, v205
	v_fmac_f32_e32 v142, v174, v206
	v_fmac_f32_e32 v143, v175, v207
	v_fmac_f32_e32 v144, v176, v208
	v_fmac_f32_e32 v145, v177, v209
	v_fmac_f32_e32 v146, v178, v210
	v_fmac_f32_e32 v147, v179, v211
	v_fmac_f32_e32 v140, v180, v196
	v_fmac_f32_e32 v141, v181, v197
	v_fmac_f32_e32 v142, v182, v198
	v_fmac_f32_e32 v143, v183, v199
	v_fmac_f32_e32 v144, v184, v200
	v_fmac_f32_e32 v145, v185, v201
	v_fmac_f32_e32 v146, v186, v202
	v_fmac_f32_e32 v147, v187, v203
	v_lshlrev_b32_e32 v150, 16, v14
	v_and_b32_e32 v151, 0xffff0000, v14
	v_mul_f32_e32 v140, v150, v140
	v_mul_f32_e32 v141, v151, v141
	v_lshlrev_b32_e32 v150, 16, v15
	v_and_b32_e32 v151, 0xffff0000, v15
	v_mul_f32_e32 v142, v150, v142
	v_mul_f32_e32 v143, v151, v143
	v_lshlrev_b32_e32 v150, 16, v16
	v_and_b32_e32 v151, 0xffff0000, v16
	v_mul_f32_e32 v144, v150, v144
	v_mul_f32_e32 v145, v151, v145
	v_lshlrev_b32_e32 v150, 16, v17
	v_and_b32_e32 v151, 0xffff0000, v17
	v_mul_f32_e32 v146, v150, v146
	v_mul_f32_e32 v147, v151, v147
	v_mul_f32_e32 v148, v140, v140
	v_fmac_f32_e32 v148, v141, v141
	v_fmac_f32_e32 v148, v142, v142
	v_fmac_f32_e32 v148, v143, v143
	v_fmac_f32_e32 v148, v144, v144
	v_fmac_f32_e32 v148, v145, v145
	v_fmac_f32_e32 v148, v146, v146
	v_fmac_f32_e32 v148, v147, v147
	v_mad_i64_i32 v[152:153], vcc, s41, v221, v[58:59]
	s_add_u32 s41, s41, 1
	global_load_dwordx4 v[14:17], v[152:153], off offset:1536
	global_load_dwordx4 v[30:33], v[152:153], off offset:2560
	s_nop 1
	v_add_f32_dpp v148, v148, v148 quad_perm:[1,0,3,2] row_mask:0xf bank_mask:0xf
	s_nop 1
	v_add_f32_dpp v148, v148, v148 quad_perm:[2,3,0,1] row_mask:0xf bank_mask:0xf
	s_nop 1
	v_add_f32_dpp v148, v148, v148 row_half_mirror row_mask:0xf bank_mask:0xf
	s_nop 1
	v_add_f32_dpp v148, v148, v148 row_mirror row_mask:0xf bank_mask:0xf
	s_nop 1
	v_add_f32_dpp v148, v148, v148 row_bcast:15 row_mask:0xa bank_mask:0xf
	s_nop 1
	v_add_f32_dpp v148, v148, v148 row_bcast:31 row_mask:0xc bank_mask:0xf
	s_nop 0
	v_readlane_b32 s0, v148, 63
	s_nop 1
	v_mov_b32_e32 v148, s0
	v_fmamk_f32 v148, v148, 0x3b000000, v162
	v_mul_f32_e32 v150, 0x4b800000, v148
	v_cmp_gt_f32_e32 vcc, s31, v148
	s_nop 1
	v_cndmask_b32_e32 v148, v148, v150, vcc
	v_rsq_f32_e32 v148, v148
	s_nop 0
	v_mul_f32_e32 v150, 0x45800000, v148
	v_cndmask_b32_e32 v149, v148, v150, vcc
	v_mul_f32_e32 v140, v149, v140
	v_mul_f32_e32 v141, v149, v141
	v_mul_f32_e32 v142, v149, v142
	v_mul_f32_e32 v143, v149, v143
	v_mul_f32_e32 v144, v149, v144
	v_mul_f32_e32 v145, v149, v145
	v_mul_f32_e32 v146, v149, v146
	v_mul_f32_e32 v147, v149, v147
	v_cvt_pk_bf16_f32 v140, v140, v141
	v_cvt_pk_bf16_f32 v141, v142, v143
	v_cvt_pk_bf16_f32 v142, v144, v145
	v_cvt_pk_bf16_f32 v143, v146, v147
	global_store_dwordx4 v[156:157], v[140:143], off offset:2048 sc1
	v_lshl_add_u64 v[156:157], v[156:157], 0, s[20:21]
	s_waitcnt vmcnt(18)
	v_lshlrev_b32_e32 v196, 16, v60
	v_and_b32_e32 v197, 0xffff0000, v60
	v_lshlrev_b32_e32 v198, 16, v61
	v_and_b32_e32 v199, 0xffff0000, v61
	v_lshlrev_b32_e32 v200, 16, v62
	v_and_b32_e32 v201, 0xffff0000, v62
	v_lshlrev_b32_e32 v202, 16, v63
	v_and_b32_e32 v203, 0xffff0000, v63
	v_mul_f32_e32 v140, v164, v196
	v_mul_f32_e32 v141, v165, v197
	v_mul_f32_e32 v142, v166, v198
	v_mul_f32_e32 v143, v167, v199
	v_mul_f32_e32 v144, v168, v200
	v_mul_f32_e32 v145, v169, v201
	v_mul_f32_e32 v146, v170, v202
	v_mul_f32_e32 v147, v171, v203
	v_fmac_f32_e32 v140, v172, v188
	v_fmac_f32_e32 v141, v173, v189
	v_fmac_f32_e32 v142, v174, v190
	v_fmac_f32_e32 v143, v175, v191
	v_fmac_f32_e32 v144, v176, v192
	v_fmac_f32_e32 v145, v177, v193
	v_fmac_f32_e32 v146, v178, v194
	v_fmac_f32_e32 v147, v179, v195
	v_fmac_f32_e32 v140, v180, v204
	v_fmac_f32_e32 v141, v181, v205
	v_fmac_f32_e32 v142, v182, v206
	v_fmac_f32_e32 v143, v183, v207
	v_fmac_f32_e32 v144, v184, v208
	v_fmac_f32_e32 v145, v185, v209
	v_fmac_f32_e32 v146, v186, v210
	v_fmac_f32_e32 v147, v187, v211
	v_lshlrev_b32_e32 v150, 16, v34
	v_and_b32_e32 v151, 0xffff0000, v34
	v_mul_f32_e32 v140, v150, v140
	v_mul_f32_e32 v141, v151, v141
	v_lshlrev_b32_e32 v150, 16, v35
	v_and_b32_e32 v151, 0xffff0000, v35
	v_mul_f32_e32 v142, v150, v142
	v_mul_f32_e32 v143, v151, v143
	v_lshlrev_b32_e32 v150, 16, v36
	v_and_b32_e32 v151, 0xffff0000, v36
	v_mul_f32_e32 v144, v150, v144
	v_mul_f32_e32 v145, v151, v145
	v_lshlrev_b32_e32 v150, 16, v37
	v_and_b32_e32 v151, 0xffff0000, v37
	v_mul_f32_e32 v146, v150, v146
	v_mul_f32_e32 v147, v151, v147
	v_mul_f32_e32 v148, v140, v140
	v_fmac_f32_e32 v148, v141, v141
	v_fmac_f32_e32 v148, v142, v142
	v_fmac_f32_e32 v148, v143, v143
	v_fmac_f32_e32 v148, v144, v144
	v_fmac_f32_e32 v148, v145, v145
	v_fmac_f32_e32 v148, v146, v146
	v_fmac_f32_e32 v148, v147, v147
	v_mad_i64_i32 v[152:153], vcc, s41, v221, v[58:59]
	s_add_u32 s41, s41, 1
	global_load_dwordx4 v[34:37], v[152:153], off offset:1536
	global_load_dwordx4 v[60:63], v[152:153], off offset:2560
	s_nop 1
	v_add_f32_dpp v148, v148, v148 quad_perm:[1,0,3,2] row_mask:0xf bank_mask:0xf
	s_nop 1
	v_add_f32_dpp v148, v148, v148 quad_perm:[2,3,0,1] row_mask:0xf bank_mask:0xf
	s_nop 1
	v_add_f32_dpp v148, v148, v148 row_half_mirror row_mask:0xf bank_mask:0xf
	s_nop 1
	v_add_f32_dpp v148, v148, v148 row_mirror row_mask:0xf bank_mask:0xf
	s_nop 1
	v_add_f32_dpp v148, v148, v148 row_bcast:15 row_mask:0xa bank_mask:0xf
	s_nop 1
	v_add_f32_dpp v148, v148, v148 row_bcast:31 row_mask:0xc bank_mask:0xf
	s_nop 0
	v_readlane_b32 s0, v148, 63
	s_nop 1
	v_mov_b32_e32 v148, s0
	v_fmamk_f32 v148, v148, 0x3b000000, v162
	v_mul_f32_e32 v150, 0x4b800000, v148
	v_cmp_gt_f32_e32 vcc, s31, v148
	s_nop 1
	v_cndmask_b32_e32 v148, v148, v150, vcc
	v_rsq_f32_e32 v148, v148
	s_nop 0
	v_mul_f32_e32 v150, 0x45800000, v148
	v_cndmask_b32_e32 v149, v148, v150, vcc
	v_mul_f32_e32 v140, v149, v140
	v_mul_f32_e32 v141, v149, v141
	v_mul_f32_e32 v142, v149, v142
	v_mul_f32_e32 v143, v149, v143
	v_mul_f32_e32 v144, v149, v144
	v_mul_f32_e32 v145, v149, v145
	v_mul_f32_e32 v146, v149, v146
	v_mul_f32_e32 v147, v149, v147
	v_cvt_pk_bf16_f32 v140, v140, v141
	v_cvt_pk_bf16_f32 v141, v142, v143
	v_cvt_pk_bf16_f32 v142, v144, v145
	v_cvt_pk_bf16_f32 v143, v146, v147
	global_store_dwordx4 v[156:157], v[140:143], off sc1
	s_waitcnt vmcnt(19)
; __device__ __forceinline__ unsigned cvt_pk_bf16(float lo, float hi) { unsigned r; asm volatile("v_cvt_pk_bf16_f32 %0, %1, %2" : "=v"(r) : "v"(lo), "v"(hi)); return r; }
; __device__ __forceinline__ float bf_lo(unsigned w) { return __uint_as_float(w << 16); }
; __device__ __forceinline__ float bf_hi(unsigned w) { return __uint_as_float(w & 0xffff0000u); }
; __global__ void __launch_bounds__(512, 2) trunk_fwd(Args args) {
;     ...
;                 for (int rr = 0; rr < 16; ++rr) {
;                     const int r = r0 + rr;
;                     const u32x4 gb = gb_n, gu = gu_n; const f32x4 pv4 = pv_n;
;                     if (rr < 15) { gb_n = *(const u32x4*)(Z + (size_t)(r + 1) * INP + 768 + c0); gu_n = *(const u32x4*)(Z + (size_t)(r + 1) * INP + 1280 + c0);
;                                    pv_n = *(const f32x4*)(pl + (size_t)(r + 1) * PLE + lane * 4); }
;                     float cv[8], uu[8]; float ss = 0.f;
; #pragma unroll
;                     for (int i = 0; i < 4; ++i) {
;                         uu[2 * i] = bf_lo(gu[i]); uu[2 * i + 1] = bf_hi(gu[i]);
;                         cv[2 * i] = bf_lo(gb[i]) * (w0[2 * i] * uu[2 * i] + w1[2 * i] * u1[2 * i] + w2[2 * i] * u2[2 * i]);
;                         cv[2 * i + 1] = bf_hi(gb[i]) * (w0[2 * i + 1] * uu[2 * i + 1] + w1[2 * i + 1] * u1[2 * i + 1] + w2[2 * i + 1] * u2[2 * i + 1]);
;                     }
; #pragma unroll
;                     for (int i = 0; i < 8; ++i) { ss += cv[i] * cv[i]; u2[i] = u1[i]; u1[i] = uu[i]; }
;                     ss = wave_sum(ss);
;                     const float rc = rsqrtf(ss * (1.0f / 512.0f) + EPS);
;                     u32x4 oc;
; #pragma unroll
;                     for (int i = 0; i < 4; ++i) oc[i] = cvt_pk_bf16(cv[2 * i] * rc, cv[2 * i + 1] * rc);
;                     *(u32x4*)(MIX + (size_t)r * 1024 + 512 + c0) = oc;
	v_lshlrev_b32_e32 v204, 16, v64
	v_and_b32_e32 v205, 0xffff0000, v64
	v_lshlrev_b32_e32 v206, 16, v65
	v_and_b32_e32 v207, 0xffff0000, v65
	v_lshlrev_b32_e32 v208, 16, v66
	v_and_b32_e32 v209, 0xffff0000, v66
	v_lshlrev_b32_e32 v210, 16, v67
	v_and_b32_e32 v211, 0xffff0000, v67
	v_mul_f32_e32 v140, v164, v204
	v_mul_f32_e32 v141, v165, v205
	v_mul_f32_e32 v142, v166, v206
	v_mul_f32_e32 v143, v167, v207
	v_mul_f32_e32 v144, v168, v208
	v_mul_f32_e32 v145, v169, v209
	v_mul_f32_e32 v146, v170, v210
	v_mul_f32_e32 v147, v171, v211
	v_fmac_f32_e32 v140, v172, v196
	v_fmac_f32_e32 v141, v173, v197
	v_fmac_f32_e32 v142, v174, v198
	v_fmac_f32_e32 v143, v175, v199
	v_fmac_f32_e32 v144, v176, v200
	v_fmac_f32_e32 v145, v177, v201
	v_fmac_f32_e32 v146, v178, v202
	v_fmac_f32_e32 v147, v179, v203
	v_fmac_f32_e32 v140, v180, v188
	v_fmac_f32_e32 v141, v181, v189
	v_fmac_f32_e32 v142, v182, v190
	v_fmac_f32_e32 v143, v183, v191
	v_fmac_f32_e32 v144, v184, v192
	v_fmac_f32_e32 v145, v185, v193
	v_fmac_f32_e32 v146, v186, v194
	v_fmac_f32_e32 v147, v187, v195
	v_lshlrev_b32_e32 v150, 16, v38
	v_and_b32_e32 v151, 0xffff0000, v38
	v_mul_f32_e32 v140, v150, v140
	v_mul_f32_e32 v141, v151, v141
	v_lshlrev_b32_e32 v150, 16, v39
	v_and_b32_e32 v151, 0xffff0000, v39
	v_mul_f32_e32 v142, v150, v142
	v_mul_f32_e32 v143, v151, v143
	v_lshlrev_b32_e32 v150, 16, v40
	v_and_b32_e32 v151, 0xffff0000, v40
	v_mul_f32_e32 v144, v150, v144
	v_mul_f32_e32 v145, v151, v145
	v_lshlrev_b32_e32 v150, 16, v41
	v_and_b32_e32 v151, 0xffff0000, v41
	v_mul_f32_e32 v146, v150, v146
	v_mul_f32_e32 v147, v151, v147
	v_mul_f32_e32 v148, v140, v140
	v_fmac_f32_e32 v148, v141, v141
	v_fmac_f32_e32 v148, v142, v142
	v_fmac_f32_e32 v148, v143, v143
	v_fmac_f32_e32 v148, v144, v144
	v_fmac_f32_e32 v148, v145, v145
	v_fmac_f32_e32 v148, v146, v146
	v_fmac_f32_e32 v148, v147, v147
	v_mad_i64_i32 v[152:153], vcc, s41, v221, v[58:59]
	s_add_u32 s41, s41, 1
	global_load_dwordx4 v[38:41], v[152:153], off offset:1536
	global_load_dwordx4 v[64:67], v[152:153], off offset:2560
	s_nop 1
	v_add_f32_dpp v148, v148, v148 quad_perm:[1,0,3,2] row_mask:0xf bank_mask:0xf
	s_nop 1
	v_add_f32_dpp v148, v148, v148 quad_perm:[2,3,0,1] row_mask:0xf bank_mask:0xf
	s_nop 1
	v_add_f32_dpp v148, v148, v148 row_half_mirror row_mask:0xf bank_mask:0xf
	s_nop 1
	v_add_f32_dpp v148, v148, v148 row_mirror row_mask:0xf bank_mask:0xf
	s_nop 1
	v_add_f32_dpp v148, v148, v148 row_bcast:15 row_mask:0xa bank_mask:0xf
	s_nop 1
	v_add_f32_dpp v148, v148, v148 row_bcast:31 row_mask:0xc bank_mask:0xf
	s_nop 0
	v_readlane_b32 s0, v148, 63
	s_nop 1
	v_mov_b32_e32 v148, s0
	v_fmamk_f32 v148, v148, 0x3b000000, v162
	v_mul_f32_e32 v150, 0x4b800000, v148
	v_cmp_gt_f32_e32 vcc, s31, v148
	s_nop 1
	v_cndmask_b32_e32 v148, v148, v150, vcc
	v_rsq_f32_e32 v148, v148
	s_nop 0
	v_mul_f32_e32 v150, 0x45800000, v148
	v_cndmask_b32_e32 v149, v148, v150, vcc
	v_mul_f32_e32 v140, v149, v140
	v_mul_f32_e32 v141, v149, v141
	v_mul_f32_e32 v142, v149, v142
	v_mul_f32_e32 v143, v149, v143
	v_mul_f32_e32 v144, v149, v144
	v_mul_f32_e32 v145, v149, v145
	v_mul_f32_e32 v146, v149, v146
	v_mul_f32_e32 v147, v149, v147
	v_cvt_pk_bf16_f32 v140, v140, v141
	v_cvt_pk_bf16_f32 v141, v142, v143
	v_cvt_pk_bf16_f32 v142, v144, v145
	v_cvt_pk_bf16_f32 v143, v146, v147
	global_store_dwordx4 v[156:157], v[140:143], off offset:2048 sc1
	v_lshl_add_u64 v[156:157], v[156:157], 0, s[20:21]
	s_waitcnt vmcnt(20)
	v_lshlrev_b32_e32 v188, 16, v68
	v_and_b32_e32 v189, 0xffff0000, v68
	v_lshlrev_b32_e32 v190, 16, v69
	v_and_b32_e32 v191, 0xffff0000, v69
	v_lshlrev_b32_e32 v192, 16, v70
	v_and_b32_e32 v193, 0xffff0000, v70
	v_lshlrev_b32_e32 v194, 16, v71
	v_and_b32_e32 v195, 0xffff0000, v71
	v_mul_f32_e32 v140, v164, v188
	v_mul_f32_e32 v141, v165, v189
	v_mul_f32_e32 v142, v166, v190
	v_mul_f32_e32 v143, v167, v191
	v_mul_f32_e32 v144, v168, v192
	v_mul_f32_e32 v145, v169, v193
	v_mul_f32_e32 v146, v170, v194
	v_mul_f32_e32 v147, v171, v195
	v_fmac_f32_e32 v140, v172, v204
	v_fmac_f32_e32 v141, v173, v205
	v_fmac_f32_e32 v142, v174, v206
	v_fmac_f32_e32 v143, v175, v207
	v_fmac_f32_e32 v144, v176, v208
	v_fmac_f32_e32 v145, v177, v209
	v_fmac_f32_e32 v146, v178, v210
	v_fmac_f32_e32 v147, v179, v211
	v_fmac_f32_e32 v140, v180, v196
	v_fmac_f32_e32 v141, v181, v197
	v_fmac_f32_e32 v142, v182, v198
	v_fmac_f32_e32 v143, v183, v199
	v_fmac_f32_e32 v144, v184, v200
	v_fmac_f32_e32 v145, v185, v201
	v_fmac_f32_e32 v146, v186, v202
	v_fmac_f32_e32 v147, v187, v203
	v_lshlrev_b32_e32 v150, 16, v42
	v_and_b32_e32 v151, 0xffff0000, v42
	v_mul_f32_e32 v140, v150, v140
	v_mul_f32_e32 v141, v151, v141
	v_lshlrev_b32_e32 v150, 16, v43
	v_and_b32_e32 v151, 0xffff0000, v43
	v_mul_f32_e32 v142, v150, v142
	v_mul_f32_e32 v143, v151, v143
	v_lshlrev_b32_e32 v150, 16, v44
	v_and_b32_e32 v151, 0xffff0000, v44
	v_mul_f32_e32 v144, v150, v144
	v_mul_f32_e32 v145, v151, v145
	v_lshlrev_b32_e32 v150, 16, v45
	v_and_b32_e32 v151, 0xffff0000, v45
	v_mul_f32_e32 v146, v150, v146
	v_mul_f32_e32 v147, v151, v147
	v_mul_f32_e32 v148, v140, v140
	v_fmac_f32_e32 v148, v141, v141
	v_fmac_f32_e32 v148, v142, v142
	v_fmac_f32_e32 v148, v143, v143
	v_fmac_f32_e32 v148, v144, v144
	v_fmac_f32_e32 v148, v145, v145
	v_fmac_f32_e32 v148, v146, v146
	v_fmac_f32_e32 v148, v147, v147
	v_mad_i64_i32 v[152:153], vcc, s41, v221, v[58:59]
	s_add_u32 s41, s41, 1
	global_load_dwordx4 v[42:45], v[152:153], off offset:1536
	global_load_dwordx4 v[68:71], v[152:153], off offset:2560
	s_nop 1
	v_add_f32_dpp v148, v148, v148 quad_perm:[1,0,3,2] row_mask:0xf bank_mask:0xf
	s_nop 1
	v_add_f32_dpp v148, v148, v148 quad_perm:[2,3,0,1] row_mask:0xf bank_mask:0xf
	s_nop 1
	v_add_f32_dpp v148, v148, v148 row_half_mirror row_mask:0xf bank_mask:0xf
	s_nop 1
	v_add_f32_dpp v148, v148, v148 row_mirror row_mask:0xf bank_mask:0xf
	s_nop 1
	v_add_f32_dpp v148, v148, v148 row_bcast:15 row_mask:0xa bank_mask:0xf
	s_nop 1
	v_add_f32_dpp v148, v148, v148 row_bcast:31 row_mask:0xc bank_mask:0xf
	s_nop 0
	v_readlane_b32 s0, v148, 63
	s_nop 1
	v_mov_b32_e32 v148, s0
	v_fmamk_f32 v148, v148, 0x3b000000, v162
	v_mul_f32_e32 v150, 0x4b800000, v148
	v_cmp_gt_f32_e32 vcc, s31, v148
	s_nop 1
	v_cndmask_b32_e32 v148, v148, v150, vcc
	v_rsq_f32_e32 v148, v148
	s_nop 0
	v_mul_f32_e32 v150, 0x45800000, v148
	v_cndmask_b32_e32 v149, v148, v150, vcc
	v_mul_f32_e32 v140, v149, v140
	v_mul_f32_e32 v141, v149, v141
	v_mul_f32_e32 v142, v149, v142
	v_mul_f32_e32 v143, v149, v143
	v_mul_f32_e32 v144, v149, v144
	v_mul_f32_e32 v145, v149, v145
	v_mul_f32_e32 v146, v149, v146
	v_mul_f32_e32 v147, v149, v147
	v_cvt_pk_bf16_f32 v140, v140, v141
	v_cvt_pk_bf16_f32 v141, v142, v143
	v_cvt_pk_bf16_f32 v142, v144, v145
	v_cvt_pk_bf16_f32 v143, v146, v147
	global_store_dwordx4 v[156:157], v[140:143], off sc1
	s_waitcnt vmcnt(21)
; __device__ __forceinline__ unsigned cvt_pk_bf16(float lo, float hi) { unsigned r; asm volatile("v_cvt_pk_bf16_f32 %0, %1, %2" : "=v"(r) : "v"(lo), "v"(hi)); return r; }
; __device__ __forceinline__ float bf_lo(unsigned w) { return __uint_as_float(w << 16); }
; __device__ __forceinline__ float bf_hi(unsigned w) { return __uint_as_float(w & 0xffff0000u); }
; __global__ void __launch_bounds__(512, 2) trunk_fwd(Args args) {
;     ...
;                 for (int rr = 0; rr < 16; ++rr) {
;                     const int r = r0 + rr;
;                     const u32x4 gb = gb_n, gu = gu_n; const f32x4 pv4 = pv_n;
;                     if (rr < 15) { gb_n = *(const u32x4*)(Z + (size_t)(r + 1) * INP + 768 + c0); gu_n = *(const u32x4*)(Z + (size_t)(r + 1) * INP + 1280 + c0);
;                                    pv_n = *(const f32x4*)(pl + (size_t)(r + 1) * PLE + lane * 4); }
;                     float cv[8], uu[8]; float ss = 0.f;
; #pragma unroll
;                     for (int i = 0; i < 4; ++i) {
;                         uu[2 * i] = bf_lo(gu[i]); uu[2 * i + 1] = bf_hi(gu[i]);
;                         cv[2 * i] = bf_lo(gb[i]) * (w0[2 * i] * uu[2 * i] + w1[2 * i] * u1[2 * i] + w2[2 * i] * u2[2 * i]);
;                         cv[2 * i + 1] = bf_hi(gb[i]) * (w0[2 * i + 1] * uu[2 * i + 1] + w1[2 * i + 1] * u1[2 * i + 1] + w2[2 * i + 1] * u2[2 * i + 1]);
;                     }
; #pragma unroll
;                     for (int i = 0; i < 8; ++i) { ss += cv[i] * cv[i]; u2[i] = u1[i]; u1[i] = uu[i]; }
;                     ss = wave_sum(ss);
;                     const float rc = rsqrtf(ss * (1.0f / 512.0f) + EPS);
;                     u32x4 oc;
; #pragma unroll
;                     for (int i = 0; i < 4; ++i) oc[i] = cvt_pk_bf16(cv[2 * i] * rc, cv[2 * i + 1] * rc);
;                     *(u32x4*)(MIX + (size_t)r * 1024 + 512 + c0) = oc;
	v_lshlrev_b32_e32 v196, 16, v72
	v_and_b32_e32 v197, 0xffff0000, v72
	v_lshlrev_b32_e32 v198, 16, v73
	v_and_b32_e32 v199, 0xffff0000, v73
	v_lshlrev_b32_e32 v200, 16, v74
	v_and_b32_e32 v201, 0xffff0000, v74
	v_lshlrev_b32_e32 v202, 16, v75
	v_and_b32_e32 v203, 0xffff0000, v75
	v_mul_f32_e32 v140, v164, v196
	v_mul_f32_e32 v141, v165, v197
	v_mul_f32_e32 v142, v166, v198
	v_mul_f32_e32 v143, v167, v199
	v_mul_f32_e32 v144, v168, v200
	v_mul_f32_e32 v145, v169, v201
	v_mul_f32_e32 v146, v170, v202
	v_mul_f32_e32 v147, v171, v203
	v_fmac_f32_e32 v140, v172, v188
	v_fmac_f32_e32 v141, v173, v189
	v_fmac_f32_e32 v142, v174, v190
	v_fmac_f32_e32 v143, v175, v191
	v_fmac_f32_e32 v144, v176, v192
	v_fmac_f32_e32 v145, v177, v193
	v_fmac_f32_e32 v146, v178, v194
	v_fmac_f32_e32 v147, v179, v195
	v_fmac_f32_e32 v140, v180, v204
	v_fmac_f32_e32 v141, v181, v205
	v_fmac_f32_e32 v142, v182, v206
	v_fmac_f32_e32 v143, v183, v207
	v_fmac_f32_e32 v144, v184, v208
	v_fmac_f32_e32 v145, v185, v209
	v_fmac_f32_e32 v146, v186, v210
	v_fmac_f32_e32 v147, v187, v211
	v_lshlrev_b32_e32 v150, 16, v46
	v_and_b32_e32 v151, 0xffff0000, v46
	v_mul_f32_e32 v140, v150, v140
	v_mul_f32_e32 v141, v151, v141
	v_lshlrev_b32_e32 v150, 16, v47
	v_and_b32_e32 v151, 0xffff0000, v47
	v_mul_f32_e32 v142, v150, v142
	v_mul_f32_e32 v143, v151, v143
	v_lshlrev_b32_e32 v150, 16, v48
	v_and_b32_e32 v151, 0xffff0000, v48
	v_mul_f32_e32 v144, v150, v144
	v_mul_f32_e32 v145, v151, v145
	v_lshlrev_b32_e32 v150, 16, v49
	v_and_b32_e32 v151, 0xffff0000, v49
	v_mul_f32_e32 v146, v150, v146
	v_mul_f32_e32 v147, v151, v147
	v_mul_f32_e32 v148, v140, v140
	v_fmac_f32_e32 v148, v141, v141
	v_fmac_f32_e32 v148, v142, v142
	v_fmac_f32_e32 v148, v143, v143
	v_fmac_f32_e32 v148, v144, v144
	v_fmac_f32_e32 v148, v145, v145
	v_fmac_f32_e32 v148, v146, v146
	v_fmac_f32_e32 v148, v147, v147
	v_mad_i64_i32 v[152:153], vcc, s41, v221, v[58:59]
	s_add_u32 s41, s41, 1
	global_load_dwordx4 v[46:49], v[152:153], off offset:1536
	global_load_dwordx4 v[72:75], v[152:153], off offset:2560
	s_nop 1
	v_add_f32_dpp v148, v148, v148 quad_perm:[1,0,3,2] row_mask:0xf bank_mask:0xf
	s_nop 1
	v_add_f32_dpp v148, v148, v148 quad_perm:[2,3,0,1] row_mask:0xf bank_mask:0xf
	s_nop 1
	v_add_f32_dpp v148, v148, v148 row_half_mirror row_mask:0xf bank_mask:0xf
	s_nop 1
	v_add_f32_dpp v148, v148, v148 row_mirror row_mask:0xf bank_mask:0xf
	s_nop 1
	v_add_f32_dpp v148, v148, v148 row_bcast:15 row_mask:0xa bank_mask:0xf
	s_nop 1
	v_add_f32_dpp v148, v148, v148 row_bcast:31 row_mask:0xc bank_mask:0xf
	s_nop 0
	v_readlane_b32 s0, v148, 63
	s_nop 1
	v_mov_b32_e32 v148, s0
	v_fmamk_f32 v148, v148, 0x3b000000, v162
	v_mul_f32_e32 v150, 0x4b800000, v148
	v_cmp_gt_f32_e32 vcc, s31, v148
	s_nop 1
	v_cndmask_b32_e32 v148, v148, v150, vcc
	v_rsq_f32_e32 v148, v148
	s_nop 0
	v_mul_f32_e32 v150, 0x45800000, v148
	v_cndmask_b32_e32 v149, v148, v150, vcc
	v_mul_f32_e32 v140, v149, v140
	v_mul_f32_e32 v141, v149, v141
	v_mul_f32_e32 v142, v149, v142
	v_mul_f32_e32 v143, v149, v143
	v_mul_f32_e32 v144, v149, v144
	v_mul_f32_e32 v145, v149, v145
	v_mul_f32_e32 v146, v149, v146
	v_mul_f32_e32 v147, v149, v147
	v_cvt_pk_bf16_f32 v140, v140, v141
	v_cvt_pk_bf16_f32 v141, v142, v143
	v_cvt_pk_bf16_f32 v142, v144, v145
	v_cvt_pk_bf16_f32 v143, v146, v147
	global_store_dwordx4 v[156:157], v[140:143], off offset:2048 sc1
	v_lshl_add_u64 v[156:157], v[156:157], 0, s[20:21]
	s_waitcnt vmcnt(22)
	v_lshlrev_b32_e32 v204, 16, v18
	v_and_b32_e32 v205, 0xffff0000, v18
	v_lshlrev_b32_e32 v206, 16, v19
	v_and_b32_e32 v207, 0xffff0000, v19
	v_lshlrev_b32_e32 v208, 16, v20
	v_and_b32_e32 v209, 0xffff0000, v20
	v_lshlrev_b32_e32 v210, 16, v21
	v_and_b32_e32 v211, 0xffff0000, v21
	v_mul_f32_e32 v140, v164, v204
	v_mul_f32_e32 v141, v165, v205
	v_mul_f32_e32 v142, v166, v206
	v_mul_f32_e32 v143, v167, v207
	v_mul_f32_e32 v144, v168, v208
	v_mul_f32_e32 v145, v169, v209
	v_mul_f32_e32 v146, v170, v210
	v_mul_f32_e32 v147, v171, v211
	v_fmac_f32_e32 v140, v172, v196
	v_fmac_f32_e32 v141, v173, v197
	v_fmac_f32_e32 v142, v174, v198
	v_fmac_f32_e32 v143, v175, v199
	v_fmac_f32_e32 v144, v176, v200
	v_fmac_f32_e32 v145, v177, v201
	v_fmac_f32_e32 v146, v178, v202
	v_fmac_f32_e32 v147, v179, v203
	v_fmac_f32_e32 v140, v180, v188
	v_fmac_f32_e32 v141, v181, v189
	v_fmac_f32_e32 v142, v182, v190
	v_fmac_f32_e32 v143, v183, v191
	v_fmac_f32_e32 v144, v184, v192
	v_fmac_f32_e32 v145, v185, v193
	v_fmac_f32_e32 v146, v186, v194
	v_fmac_f32_e32 v147, v187, v195
	v_lshlrev_b32_e32 v150, 16, v2
	v_and_b32_e32 v151, 0xffff0000, v2
	v_mul_f32_e32 v140, v150, v140
	v_mul_f32_e32 v141, v151, v141
	v_lshlrev_b32_e32 v150, 16, v3
	v_and_b32_e32 v151, 0xffff0000, v3
	v_mul_f32_e32 v142, v150, v142
	v_mul_f32_e32 v143, v151, v143
	v_lshlrev_b32_e32 v150, 16, v4
	v_and_b32_e32 v151, 0xffff0000, v4
	v_mul_f32_e32 v144, v150, v144
	v_mul_f32_e32 v145, v151, v145
	v_lshlrev_b32_e32 v150, 16, v5
	v_and_b32_e32 v151, 0xffff0000, v5
	v_mul_f32_e32 v146, v150, v146
	v_mul_f32_e32 v147, v151, v147
	v_mul_f32_e32 v148, v140, v140
	v_fmac_f32_e32 v148, v141, v141
	v_fmac_f32_e32 v148, v142, v142
	v_fmac_f32_e32 v148, v143, v143
	v_fmac_f32_e32 v148, v144, v144
	v_fmac_f32_e32 v148, v145, v145
	v_fmac_f32_e32 v148, v146, v146
	v_fmac_f32_e32 v148, v147, v147
	s_nop 1
	v_add_f32_dpp v148, v148, v148 quad_perm:[1,0,3,2] row_mask:0xf bank_mask:0xf
	s_nop 1
	v_add_f32_dpp v148, v148, v148 quad_perm:[2,3,0,1] row_mask:0xf bank_mask:0xf
	s_nop 1
	v_add_f32_dpp v148, v148, v148 row_half_mirror row_mask:0xf bank_mask:0xf
	s_nop 1
	v_add_f32_dpp v148, v148, v148 row_mirror row_mask:0xf bank_mask:0xf
	s_nop 1
	v_add_f32_dpp v148, v148, v148 row_bcast:15 row_mask:0xa bank_mask:0xf
	s_nop 1
	v_add_f32_dpp v148, v148, v148 row_bcast:31 row_mask:0xc bank_mask:0xf
	s_nop 0
	v_readlane_b32 s0, v148, 63
	s_nop 1
	v_mov_b32_e32 v148, s0
	v_fmamk_f32 v148, v148, 0x3b000000, v162
	v_mul_f32_e32 v150, 0x4b800000, v148
	v_cmp_gt_f32_e32 vcc, s31, v148
	s_nop 1
	v_cndmask_b32_e32 v148, v148, v150, vcc
	v_rsq_f32_e32 v148, v148
	s_nop 0
	v_mul_f32_e32 v150, 0x45800000, v148
	v_cndmask_b32_e32 v149, v148, v150, vcc
	v_mul_f32_e32 v140, v149, v140
	v_mul_f32_e32 v141, v149, v141
	v_mul_f32_e32 v142, v149, v142
	v_mul_f32_e32 v143, v149, v143
	v_mul_f32_e32 v144, v149, v144
	v_mul_f32_e32 v145, v149, v145
	v_mul_f32_e32 v146, v149, v146
	v_mul_f32_e32 v147, v149, v147
	v_cvt_pk_bf16_f32 v140, v140, v141
	v_cvt_pk_bf16_f32 v141, v142, v143
	v_cvt_pk_bf16_f32 v142, v144, v145
	v_cvt_pk_bf16_f32 v143, v146, v147
	global_store_dwordx4 v[156:157], v[140:143], off sc1
	s_waitcnt vmcnt(20)
; __device__ __forceinline__ unsigned cvt_pk_bf16(float lo, float hi) { unsigned r; asm volatile("v_cvt_pk_bf16_f32 %0, %1, %2" : "=v"(r) : "v"(lo), "v"(hi)); return r; }
; __device__ __forceinline__ float bf_lo(unsigned w) { return __uint_as_float(w << 16); }
; __device__ __forceinline__ float bf_hi(unsigned w) { return __uint_as_float(w & 0xffff0000u); }
; __global__ void __launch_bounds__(512, 2) trunk_fwd(Args args) {
;     ...
;                 for (int rr = 0; rr < 16; ++rr) {
;                     const int r = r0 + rr;
;                     const u32x4 gb = gb_n, gu = gu_n; const f32x4 pv4 = pv_n;
;                     if (rr < 15) { gb_n = *(const u32x4*)(Z + (size_t)(r + 1) * INP + 768 + c0); gu_n = *(const u32x4*)(Z + (size_t)(r + 1) * INP + 1280 + c0);
;                                    pv_n = *(const f32x4*)(pl + (size_t)(r + 1) * PLE + lane * 4); }
;                     float cv[8], uu[8]; float ss = 0.f;
; #pragma unroll
;                     for (int i = 0; i < 4; ++i) {
;                         uu[2 * i] = bf_lo(gu[i]); uu[2 * i + 1] = bf_hi(gu[i]);
;                         cv[2 * i] = bf_lo(gb[i]) * (w0[2 * i] * uu[2 * i] + w1[2 * i] * u1[2 * i] + w2[2 * i] * u2[2 * i]);
;                         cv[2 * i + 1] = bf_hi(gb[i]) * (w0[2 * i + 1] * uu[2 * i + 1] + w1[2 * i + 1] * u1[2 * i + 1] + w2[2 * i + 1] * u2[2 * i + 1]);
;                     }
; #pragma unroll
;                     for (int i = 0; i < 8; ++i) { ss += cv[i] * cv[i]; u2[i] = u1[i]; u1[i] = uu[i]; }
;                     ss = wave_sum(ss);
;                     const float rc = rsqrtf(ss * (1.0f / 512.0f) + EPS);
;                     u32x4 oc;
; #pragma unroll
;                     for (int i = 0; i < 4; ++i) oc[i] = cvt_pk_bf16(cv[2 * i] * rc, cv[2 * i + 1] * rc);
;                     *(u32x4*)(MIX + (size_t)r * 1024 + 512 + c0) = oc;
	v_lshlrev_b32_e32 v188, 16, v22
	v_and_b32_e32 v189, 0xffff0000, v22
	v_lshlrev_b32_e32 v190, 16, v23
	v_and_b32_e32 v191, 0xffff0000, v23
	v_lshlrev_b32_e32 v192, 16, v24
	v_and_b32_e32 v193, 0xffff0000, v24
	v_lshlrev_b32_e32 v194, 16, v25
	v_and_b32_e32 v195, 0xffff0000, v25
	v_mul_f32_e32 v140, v164, v188
	v_mul_f32_e32 v141, v165, v189
	v_mul_f32_e32 v142, v166, v190
	v_mul_f32_e32 v143, v167, v191
	v_mul_f32_e32 v144, v168, v192
	v_mul_f32_e32 v145, v169, v193
	v_mul_f32_e32 v146, v170, v194
	v_mul_f32_e32 v147, v171, v195
	v_fmac_f32_e32 v140, v172, v204
	v_fmac_f32_e32 v141, v173, v205
	v_fmac_f32_e32 v142, v174, v206
	v_fmac_f32_e32 v143, v175, v207
	v_fmac_f32_e32 v144, v176, v208
	v_fmac_f32_e32 v145, v177, v209
	v_fmac_f32_e32 v146, v178, v210
	v_fmac_f32_e32 v147, v179, v211
	v_fmac_f32_e32 v140, v180, v196
	v_fmac_f32_e32 v141, v181, v197
	v_fmac_f32_e32 v142, v182, v198
	v_fmac_f32_e32 v143, v183, v199
	v_fmac_f32_e32 v144, v184, v200
	v_fmac_f32_e32 v145, v185, v201
	v_fmac_f32_e32 v146, v186, v202
	v_fmac_f32_e32 v147, v187, v203
	v_lshlrev_b32_e32 v150, 16, v6
	v_and_b32_e32 v151, 0xffff0000, v6
	v_mul_f32_e32 v140, v150, v140
	v_mul_f32_e32 v141, v151, v141
	v_lshlrev_b32_e32 v150, 16, v7
	v_and_b32_e32 v151, 0xffff0000, v7
	v_mul_f32_e32 v142, v150, v142
	v_mul_f32_e32 v143, v151, v143
	v_lshlrev_b32_e32 v150, 16, v8
	v_and_b32_e32 v151, 0xffff0000, v8
	v_mul_f32_e32 v144, v150, v144
	v_mul_f32_e32 v145, v151, v145
	v_lshlrev_b32_e32 v150, 16, v9
	v_and_b32_e32 v151, 0xffff0000, v9
	v_mul_f32_e32 v146, v150, v146
	v_mul_f32_e32 v147, v151, v147
	v_mul_f32_e32 v148, v140, v140
	v_fmac_f32_e32 v148, v141, v141
	v_fmac_f32_e32 v148, v142, v142
	v_fmac_f32_e32 v148, v143, v143
	v_fmac_f32_e32 v148, v144, v144
	v_fmac_f32_e32 v148, v145, v145
	v_fmac_f32_e32 v148, v146, v146
	v_fmac_f32_e32 v148, v147, v147
	s_nop 1
	v_add_f32_dpp v148, v148, v148 quad_perm:[1,0,3,2] row_mask:0xf bank_mask:0xf
	s_nop 1
	v_add_f32_dpp v148, v148, v148 quad_perm:[2,3,0,1] row_mask:0xf bank_mask:0xf
	s_nop 1
	v_add_f32_dpp v148, v148, v148 row_half_mirror row_mask:0xf bank_mask:0xf
	s_nop 1
	v_add_f32_dpp v148, v148, v148 row_mirror row_mask:0xf bank_mask:0xf
	s_nop 1
	v_add_f32_dpp v148, v148, v148 row_bcast:15 row_mask:0xa bank_mask:0xf
	s_nop 1
	v_add_f32_dpp v148, v148, v148 row_bcast:31 row_mask:0xc bank_mask:0xf
	s_nop 0
	v_readlane_b32 s0, v148, 63
	s_nop 1
	v_mov_b32_e32 v148, s0
	v_fmamk_f32 v148, v148, 0x3b000000, v162
	v_mul_f32_e32 v150, 0x4b800000, v148
	v_cmp_gt_f32_e32 vcc, s31, v148
	s_nop 1
	v_cndmask_b32_e32 v148, v148, v150, vcc
	v_rsq_f32_e32 v148, v148
	s_nop 0
	v_mul_f32_e32 v150, 0x45800000, v148
	v_cndmask_b32_e32 v149, v148, v150, vcc
	v_mul_f32_e32 v140, v149, v140
	v_mul_f32_e32 v141, v149, v141
	v_mul_f32_e32 v142, v149, v142
	v_mul_f32_e32 v143, v149, v143
	v_mul_f32_e32 v144, v149, v144
	v_mul_f32_e32 v145, v149, v145
	v_mul_f32_e32 v146, v149, v146
	v_mul_f32_e32 v147, v149, v147
	v_cvt_pk_bf16_f32 v140, v140, v141
	v_cvt_pk_bf16_f32 v141, v142, v143
	v_cvt_pk_bf16_f32 v142, v144, v145
	v_cvt_pk_bf16_f32 v143, v146, v147
	global_store_dwordx4 v[156:157], v[140:143], off offset:2048 sc1
	v_lshl_add_u64 v[156:157], v[156:157], 0, s[20:21]
	s_waitcnt vmcnt(18)
	v_lshlrev_b32_e32 v196, 16, v26
	v_and_b32_e32 v197, 0xffff0000, v26
	v_lshlrev_b32_e32 v198, 16, v27
	v_and_b32_e32 v199, 0xffff0000, v27
	v_lshlrev_b32_e32 v200, 16, v28
	v_and_b32_e32 v201, 0xffff0000, v28
	v_lshlrev_b32_e32 v202, 16, v29
	v_and_b32_e32 v203, 0xffff0000, v29
	v_mul_f32_e32 v140, v164, v196
	v_mul_f32_e32 v141, v165, v197
	v_mul_f32_e32 v142, v166, v198
	v_mul_f32_e32 v143, v167, v199
	v_mul_f32_e32 v144, v168, v200
	v_mul_f32_e32 v145, v169, v201
	v_mul_f32_e32 v146, v170, v202
	v_mul_f32_e32 v147, v171, v203
	v_fmac_f32_e32 v140, v172, v188
	v_fmac_f32_e32 v141, v173, v189
	v_fmac_f32_e32 v142, v174, v190
	v_fmac_f32_e32 v143, v175, v191
	v_fmac_f32_e32 v144, v176, v192
	v_fmac_f32_e32 v145, v177, v193
	v_fmac_f32_e32 v146, v178, v194
	v_fmac_f32_e32 v147, v179, v195
	v_fmac_f32_e32 v140, v180, v204
	v_fmac_f32_e32 v141, v181, v205
	v_fmac_f32_e32 v142, v182, v206
	v_fmac_f32_e32 v143, v183, v207
	v_fmac_f32_e32 v144, v184, v208
	v_fmac_f32_e32 v145, v185, v209
	v_fmac_f32_e32 v146, v186, v210
	v_fmac_f32_e32 v147, v187, v211
	v_lshlrev_b32_e32 v150, 16, v10
	v_and_b32_e32 v151, 0xffff0000, v10
	v_mul_f32_e32 v140, v150, v140
	v_mul_f32_e32 v141, v151, v141
	v_lshlrev_b32_e32 v150, 16, v11
	v_and_b32_e32 v151, 0xffff0000, v11
	v_mul_f32_e32 v142, v150, v142
	v_mul_f32_e32 v143, v151, v143
	v_lshlrev_b32_e32 v150, 16, v12
	v_and_b32_e32 v151, 0xffff0000, v12
	v_mul_f32_e32 v144, v150, v144
	v_mul_f32_e32 v145, v151, v145
	v_lshlrev_b32_e32 v150, 16, v13
	v_and_b32_e32 v151, 0xffff0000, v13
	v_mul_f32_e32 v146, v150, v146
	v_mul_f32_e32 v147, v151, v147
	v_mul_f32_e32 v148, v140, v140
	v_fmac_f32_e32 v148, v141, v141
	v_fmac_f32_e32 v148, v142, v142
	v_fmac_f32_e32 v148, v143, v143
	v_fmac_f32_e32 v148, v144, v144
	v_fmac_f32_e32 v148, v145, v145
	v_fmac_f32_e32 v148, v146, v146
	v_fmac_f32_e32 v148, v147, v147
	s_nop 1
	v_add_f32_dpp v148, v148, v148 quad_perm:[1,0,3,2] row_mask:0xf bank_mask:0xf
	s_nop 1
	v_add_f32_dpp v148, v148, v148 quad_perm:[2,3,0,1] row_mask:0xf bank_mask:0xf
	s_nop 1
	v_add_f32_dpp v148, v148, v148 row_half_mirror row_mask:0xf bank_mask:0xf
	s_nop 1
	v_add_f32_dpp v148, v148, v148 row_mirror row_mask:0xf bank_mask:0xf
	s_nop 1
	v_add_f32_dpp v148, v148, v148 row_bcast:15 row_mask:0xa bank_mask:0xf
	s_nop 1
	v_add_f32_dpp v148, v148, v148 row_bcast:31 row_mask:0xc bank_mask:0xf
	s_nop 0
	v_readlane_b32 s0, v148, 63
	s_nop 1
	v_mov_b32_e32 v148, s0
	v_fmamk_f32 v148, v148, 0x3b000000, v162
	v_mul_f32_e32 v150, 0x4b800000, v148
	v_cmp_gt_f32_e32 vcc, s31, v148
	s_nop 1
	v_cndmask_b32_e32 v148, v148, v150, vcc
	v_rsq_f32_e32 v148, v148
	s_nop 0
	v_mul_f32_e32 v150, 0x45800000, v148
	v_cndmask_b32_e32 v149, v148, v150, vcc
	v_mul_f32_e32 v140, v149, v140
	v_mul_f32_e32 v141, v149, v141
	v_mul_f32_e32 v142, v149, v142
	v_mul_f32_e32 v143, v149, v143
	v_mul_f32_e32 v144, v149, v144
	v_mul_f32_e32 v145, v149, v145
	v_mul_f32_e32 v146, v149, v146
	v_mul_f32_e32 v147, v149, v147
	v_cvt_pk_bf16_f32 v140, v140, v141
	v_cvt_pk_bf16_f32 v141, v142, v143
	v_cvt_pk_bf16_f32 v142, v144, v145
	v_cvt_pk_bf16_f32 v143, v146, v147
	global_store_dwordx4 v[156:157], v[140:143], off sc1
	s_waitcnt vmcnt(16)
; __device__ __forceinline__ unsigned cvt_pk_bf16(float lo, float hi) { unsigned r; asm volatile("v_cvt_pk_bf16_f32 %0, %1, %2" : "=v"(r) : "v"(lo), "v"(hi)); return r; }
; __device__ __forceinline__ float bf_lo(unsigned w) { return __uint_as_float(w << 16); }
; __device__ __forceinline__ float bf_hi(unsigned w) { return __uint_as_float(w & 0xffff0000u); }
; __global__ void __launch_bounds__(512, 2) trunk_fwd(Args args) {
;     ...
;                 for (int rr = 0; rr < 16; ++rr) {
;                     const int r = r0 + rr;
;                     const u32x4 gb = gb_n, gu = gu_n; const f32x4 pv4 = pv_n;
;                     if (rr < 15) { gb_n = *(const u32x4*)(Z + (size_t)(r + 1) * INP + 768 + c0); gu_n = *(const u32x4*)(Z + (size_t)(r + 1) * INP + 1280 + c0);
;                                    pv_n = *(const f32x4*)(pl + (size_t)(r + 1) * PLE + lane * 4); }
;                     float cv[8], uu[8]; float ss = 0.f;
; #pragma unroll
;                     for (int i = 0; i < 4; ++i) {
;                         uu[2 * i] = bf_lo(gu[i]); uu[2 * i + 1] = bf_hi(gu[i]);
;                         cv[2 * i] = bf_lo(gb[i]) * (w0[2 * i] * uu[2 * i] + w1[2 * i] * u1[2 * i] + w2[2 * i] * u2[2 * i]);
;                         cv[2 * i + 1] = bf_hi(gb[i]) * (w0[2 * i + 1] * uu[2 * i + 1] + w1[2 * i + 1] * u1[2 * i + 1] + w2[2 * i + 1] * u2[2 * i + 1]);
;                     }
; #pragma unroll
;                     for (int i = 0; i < 8; ++i) { ss += cv[i] * cv[i]; u2[i] = u1[i]; u1[i] = uu[i]; }
;                     ss = wave_sum(ss);
;                     const float rc = rsqrtf(ss * (1.0f / 512.0f) + EPS);
;                     u32x4 oc;
; #pragma unroll
;                     for (int i = 0; i < 4; ++i) oc[i] = cvt_pk_bf16(cv[2 * i] * rc, cv[2 * i + 1] * rc);
;                     *(u32x4*)(MIX + (size_t)r * 1024 + 512 + c0) = oc;
	v_lshlrev_b32_e32 v204, 16, v30
	v_and_b32_e32 v205, 0xffff0000, v30
	v_lshlrev_b32_e32 v206, 16, v31
	v_and_b32_e32 v207, 0xffff0000, v31
	v_lshlrev_b32_e32 v208, 16, v32
	v_and_b32_e32 v209, 0xffff0000, v32
	v_lshlrev_b32_e32 v210, 16, v33
	v_and_b32_e32 v211, 0xffff0000, v33
	v_mul_f32_e32 v140, v164, v204
	v_mul_f32_e32 v141, v165, v205
	v_mul_f32_e32 v142, v166, v206
	v_mul_f32_e32 v143, v167, v207
	v_mul_f32_e32 v144, v168, v208
	v_mul_f32_e32 v145, v169, v209
	v_mul_f32_e32 v146, v170, v210
	v_mul_f32_e32 v147, v171, v211
	v_fmac_f32_e32 v140, v172, v196
	v_fmac_f32_e32 v141, v173, v197
	v_fmac_f32_e32 v142, v174, v198
	v_fmac_f32_e32 v143, v175, v199
	v_fmac_f32_e32 v144, v176, v200
	v_fmac_f32_e32 v145, v177, v201
	v_fmac_f32_e32 v146, v178, v202
	v_fmac_f32_e32 v147, v179, v203
	v_fmac_f32_e32 v140, v180, v188
	v_fmac_f32_e32 v141, v181, v189
	v_fmac_f32_e32 v142, v182, v190
	v_fmac_f32_e32 v143, v183, v191
	v_fmac_f32_e32 v144, v184, v192
	v_fmac_f32_e32 v145, v185, v193
	v_fmac_f32_e32 v146, v186, v194
	v_fmac_f32_e32 v147, v187, v195
	v_lshlrev_b32_e32 v150, 16, v14
	v_and_b32_e32 v151, 0xffff0000, v14
	v_mul_f32_e32 v140, v150, v140
	v_mul_f32_e32 v141, v151, v141
	v_lshlrev_b32_e32 v150, 16, v15
	v_and_b32_e32 v151, 0xffff0000, v15
	v_mul_f32_e32 v142, v150, v142
	v_mul_f32_e32 v143, v151, v143
	v_lshlrev_b32_e32 v150, 16, v16
	v_and_b32_e32 v151, 0xffff0000, v16
	v_mul_f32_e32 v144, v150, v144
	v_mul_f32_e32 v145, v151, v145
	v_lshlrev_b32_e32 v150, 16, v17
	v_and_b32_e32 v151, 0xffff0000, v17
	v_mul_f32_e32 v146, v150, v146
	v_mul_f32_e32 v147, v151, v147
	v_mul_f32_e32 v148, v140, v140
	v_fmac_f32_e32 v148, v141, v141
	v_fmac_f32_e32 v148, v142, v142
	v_fmac_f32_e32 v148, v143, v143
	v_fmac_f32_e32 v148, v144, v144
	v_fmac_f32_e32 v148, v145, v145
	v_fmac_f32_e32 v148, v146, v146
	v_fmac_f32_e32 v148, v147, v147
	s_nop 1
	v_add_f32_dpp v148, v148, v148 quad_perm:[1,0,3,2] row_mask:0xf bank_mask:0xf
	s_nop 1
	v_add_f32_dpp v148, v148, v148 quad_perm:[2,3,0,1] row_mask:0xf bank_mask:0xf
	s_nop 1
	v_add_f32_dpp v148, v148, v148 row_half_mirror row_mask:0xf bank_mask:0xf
	s_nop 1
	v_add_f32_dpp v148, v148, v148 row_mirror row_mask:0xf bank_mask:0xf
	s_nop 1
	v_add_f32_dpp v148, v148, v148 row_bcast:15 row_mask:0xa bank_mask:0xf
	s_nop 1
	v_add_f32_dpp v148, v148, v148 row_bcast:31 row_mask:0xc bank_mask:0xf
	s_nop 0
	v_readlane_b32 s0, v148, 63
	s_nop 1
	v_mov_b32_e32 v148, s0
	v_fmamk_f32 v148, v148, 0x3b000000, v162
	v_mul_f32_e32 v150, 0x4b800000, v148
	v_cmp_gt_f32_e32 vcc, s31, v148
	s_nop 1
	v_cndmask_b32_e32 v148, v148, v150, vcc
	v_rsq_f32_e32 v148, v148
	s_nop 0
	v_mul_f32_e32 v150, 0x45800000, v148
	v_cndmask_b32_e32 v149, v148, v150, vcc
	v_mul_f32_e32 v140, v149, v140
	v_mul_f32_e32 v141, v149, v141
	v_mul_f32_e32 v142, v149, v142
	v_mul_f32_e32 v143, v149, v143
	v_mul_f32_e32 v144, v149, v144
	v_mul_f32_e32 v145, v149, v145
	v_mul_f32_e32 v146, v149, v146
	v_mul_f32_e32 v147, v149, v147
	v_cvt_pk_bf16_f32 v140, v140, v141
	v_cvt_pk_bf16_f32 v141, v142, v143
	v_cvt_pk_bf16_f32 v142, v144, v145
	v_cvt_pk_bf16_f32 v143, v146, v147
	global_store_dwordx4 v[156:157], v[140:143], off offset:2048 sc1
	v_lshl_add_u64 v[156:157], v[156:157], 0, s[20:21]
	s_waitcnt vmcnt(14)
	v_lshlrev_b32_e32 v188, 16, v60
	v_and_b32_e32 v189, 0xffff0000, v60
	v_lshlrev_b32_e32 v190, 16, v61
	v_and_b32_e32 v191, 0xffff0000, v61
	v_lshlrev_b32_e32 v192, 16, v62
	v_and_b32_e32 v193, 0xffff0000, v62
	v_lshlrev_b32_e32 v194, 16, v63
	v_and_b32_e32 v195, 0xffff0000, v63
	v_mul_f32_e32 v140, v164, v188
	v_mul_f32_e32 v141, v165, v189
	v_mul_f32_e32 v142, v166, v190
	v_mul_f32_e32 v143, v167, v191
	v_mul_f32_e32 v144, v168, v192
	v_mul_f32_e32 v145, v169, v193
	v_mul_f32_e32 v146, v170, v194
	v_mul_f32_e32 v147, v171, v195
	v_fmac_f32_e32 v140, v172, v204
	v_fmac_f32_e32 v141, v173, v205
	v_fmac_f32_e32 v142, v174, v206
	v_fmac_f32_e32 v143, v175, v207
	v_fmac_f32_e32 v144, v176, v208
	v_fmac_f32_e32 v145, v177, v209
	v_fmac_f32_e32 v146, v178, v210
	v_fmac_f32_e32 v147, v179, v211
	v_fmac_f32_e32 v140, v180, v196
	v_fmac_f32_e32 v141, v181, v197
	v_fmac_f32_e32 v142, v182, v198
	v_fmac_f32_e32 v143, v183, v199
	v_fmac_f32_e32 v144, v184, v200
	v_fmac_f32_e32 v145, v185, v201
	v_fmac_f32_e32 v146, v186, v202
	v_fmac_f32_e32 v147, v187, v203
	v_lshlrev_b32_e32 v150, 16, v34
	v_and_b32_e32 v151, 0xffff0000, v34
	v_mul_f32_e32 v140, v150, v140
	v_mul_f32_e32 v141, v151, v141
	v_lshlrev_b32_e32 v150, 16, v35
	v_and_b32_e32 v151, 0xffff0000, v35
	v_mul_f32_e32 v142, v150, v142
	v_mul_f32_e32 v143, v151, v143
	v_lshlrev_b32_e32 v150, 16, v36
	v_and_b32_e32 v151, 0xffff0000, v36
	v_mul_f32_e32 v144, v150, v144
	v_mul_f32_e32 v145, v151, v145
	v_lshlrev_b32_e32 v150, 16, v37
	v_and_b32_e32 v151, 0xffff0000, v37
	v_mul_f32_e32 v146, v150, v146
	v_mul_f32_e32 v147, v151, v147
	v_mul_f32_e32 v148, v140, v140
	v_fmac_f32_e32 v148, v141, v141
	v_fmac_f32_e32 v148, v142, v142
	v_fmac_f32_e32 v148, v143, v143
	v_fmac_f32_e32 v148, v144, v144
	v_fmac_f32_e32 v148, v145, v145
	v_fmac_f32_e32 v148, v146, v146
	v_fmac_f32_e32 v148, v147, v147
	s_nop 1
	v_add_f32_dpp v148, v148, v148 quad_perm:[1,0,3,2] row_mask:0xf bank_mask:0xf
	s_nop 1
	v_add_f32_dpp v148, v148, v148 quad_perm:[2,3,0,1] row_mask:0xf bank_mask:0xf
	s_nop 1
	v_add_f32_dpp v148, v148, v148 row_half_mirror row_mask:0xf bank_mask:0xf
	s_nop 1
	v_add_f32_dpp v148, v148, v148 row_mirror row_mask:0xf bank_mask:0xf
	s_nop 1
	v_add_f32_dpp v148, v148, v148 row_bcast:15 row_mask:0xa bank_mask:0xf
	s_nop 1
	v_add_f32_dpp v148, v148, v148 row_bcast:31 row_mask:0xc bank_mask:0xf
	s_nop 0
	v_readlane_b32 s0, v148, 63
	s_nop 1
	v_mov_b32_e32 v148, s0
	v_fmamk_f32 v148, v148, 0x3b000000, v162
	v_mul_f32_e32 v150, 0x4b800000, v148
	v_cmp_gt_f32_e32 vcc, s31, v148
	s_nop 1
	v_cndmask_b32_e32 v148, v148, v150, vcc
	v_rsq_f32_e32 v148, v148
	s_nop 0
	v_mul_f32_e32 v150, 0x45800000, v148
	v_cndmask_b32_e32 v149, v148, v150, vcc
	v_mul_f32_e32 v140, v149, v140
	v_mul_f32_e32 v141, v149, v141
	v_mul_f32_e32 v142, v149, v142
	v_mul_f32_e32 v143, v149, v143
	v_mul_f32_e32 v144, v149, v144
	v_mul_f32_e32 v145, v149, v145
	v_mul_f32_e32 v146, v149, v146
	v_mul_f32_e32 v147, v149, v147
	v_cvt_pk_bf16_f32 v140, v140, v141
	v_cvt_pk_bf16_f32 v141, v142, v143
	v_cvt_pk_bf16_f32 v142, v144, v145
	v_cvt_pk_bf16_f32 v143, v146, v147
	global_store_dwordx4 v[156:157], v[140:143], off sc1
	s_waitcnt vmcnt(12)
; __device__ __forceinline__ unsigned cvt_pk_bf16(float lo, float hi) { unsigned r; asm volatile("v_cvt_pk_bf16_f32 %0, %1, %2" : "=v"(r) : "v"(lo), "v"(hi)); return r; }
; __device__ __forceinline__ float bf_lo(unsigned w) { return __uint_as_float(w << 16); }
; __device__ __forceinline__ float bf_hi(unsigned w) { return __uint_as_float(w & 0xffff0000u); }
; __global__ void __launch_bounds__(512, 2) trunk_fwd(Args args) {
;     ...
;                 for (int rr = 0; rr < 16; ++rr) {
;                     const int r = r0 + rr;
;                     const u32x4 gb = gb_n, gu = gu_n; const f32x4 pv4 = pv_n;
;                     if (rr < 15) { gb_n = *(const u32x4*)(Z + (size_t)(r + 1) * INP + 768 + c0); gu_n = *(const u32x4*)(Z + (size_t)(r + 1) * INP + 1280 + c0);
;                                    pv_n = *(const f32x4*)(pl + (size_t)(r + 1) * PLE + lane * 4); }
;                     float cv[8], uu[8]; float ss = 0.f;
; #pragma unroll
;                     for (int i = 0; i < 4; ++i) {
;                         uu[2 * i] = bf_lo(gu[i]); uu[2 * i + 1] = bf_hi(gu[i]);
;                         cv[2 * i] = bf_lo(gb[i]) * (w0[2 * i] * uu[2 * i] + w1[2 * i] * u1[2 * i] + w2[2 * i] * u2[2 * i]);
;                         cv[2 * i + 1] = bf_hi(gb[i]) * (w0[2 * i + 1] * uu[2 * i + 1] + w1[2 * i + 1] * u1[2 * i + 1] + w2[2 * i + 1] * u2[2 * i + 1]);
;                     }
; #pragma unroll
;                     for (int i = 0; i < 8; ++i) { ss += cv[i] * cv[i]; u2[i] = u1[i]; u1[i] = uu[i]; }
;                     ss = wave_sum(ss);
;                     const float rc = rsqrtf(ss * (1.0f / 512.0f) + EPS);
;                     u32x4 oc;
; #pragma unroll
;                     for (int i = 0; i < 4; ++i) oc[i] = cvt_pk_bf16(cv[2 * i] * rc, cv[2 * i + 1] * rc);
;                     *(u32x4*)(MIX + (size_t)r * 1024 + 512 + c0) = oc;
	v_lshlrev_b32_e32 v196, 16, v64
	v_and_b32_e32 v197, 0xffff0000, v64
	v_lshlrev_b32_e32 v198, 16, v65
	v_and_b32_e32 v199, 0xffff0000, v65
	v_lshlrev_b32_e32 v200, 16, v66
	v_and_b32_e32 v201, 0xffff0000, v66
	v_lshlrev_b32_e32 v202, 16, v67
	v_and_b32_e32 v203, 0xffff0000, v67
	v_mul_f32_e32 v140, v164, v196
	v_mul_f32_e32 v141, v165, v197
	v_mul_f32_e32 v142, v166, v198
	v_mul_f32_e32 v143, v167, v199
	v_mul_f32_e32 v144, v168, v200
	v_mul_f32_e32 v145, v169, v201
	v_mul_f32_e32 v146, v170, v202
	v_mul_f32_e32 v147, v171, v203
	v_fmac_f32_e32 v140, v172, v188
	v_fmac_f32_e32 v141, v173, v189
	v_fmac_f32_e32 v142, v174, v190
	v_fmac_f32_e32 v143, v175, v191
	v_fmac_f32_e32 v144, v176, v192
	v_fmac_f32_e32 v145, v177, v193
	v_fmac_f32_e32 v146, v178, v194
	v_fmac_f32_e32 v147, v179, v195
	v_fmac_f32_e32 v140, v180, v204
	v_fmac_f32_e32 v141, v181, v205
	v_fmac_f32_e32 v142, v182, v206
	v_fmac_f32_e32 v143, v183, v207
	v_fmac_f32_e32 v144, v184, v208
	v_fmac_f32_e32 v145, v185, v209
	v_fmac_f32_e32 v146, v186, v210
	v_fmac_f32_e32 v147, v187, v211
	v_lshlrev_b32_e32 v150, 16, v38
	v_and_b32_e32 v151, 0xffff0000, v38
	v_mul_f32_e32 v140, v150, v140
	v_mul_f32_e32 v141, v151, v141
	v_lshlrev_b32_e32 v150, 16, v39
	v_and_b32_e32 v151, 0xffff0000, v39
	v_mul_f32_e32 v142, v150, v142
	v_mul_f32_e32 v143, v151, v143
	v_lshlrev_b32_e32 v150, 16, v40
	v_and_b32_e32 v151, 0xffff0000, v40
	v_mul_f32_e32 v144, v150, v144
	v_mul_f32_e32 v145, v151, v145
	v_lshlrev_b32_e32 v150, 16, v41
	v_and_b32_e32 v151, 0xffff0000, v41
	v_mul_f32_e32 v146, v150, v146
	v_mul_f32_e32 v147, v151, v147
	v_mul_f32_e32 v148, v140, v140
	v_fmac_f32_e32 v148, v141, v141
	v_fmac_f32_e32 v148, v142, v142
	v_fmac_f32_e32 v148, v143, v143
	v_fmac_f32_e32 v148, v144, v144
	v_fmac_f32_e32 v148, v145, v145
	v_fmac_f32_e32 v148, v146, v146
	v_fmac_f32_e32 v148, v147, v147
	s_nop 1
	v_add_f32_dpp v148, v148, v148 quad_perm:[1,0,3,2] row_mask:0xf bank_mask:0xf
	s_nop 1
	v_add_f32_dpp v148, v148, v148 quad_perm:[2,3,0,1] row_mask:0xf bank_mask:0xf
	s_nop 1
	v_add_f32_dpp v148, v148, v148 row_half_mirror row_mask:0xf bank_mask:0xf
	s_nop 1
	v_add_f32_dpp v148, v148, v148 row_mirror row_mask:0xf bank_mask:0xf
	s_nop 1
	v_add_f32_dpp v148, v148, v148 row_bcast:15 row_mask:0xa bank_mask:0xf
	s_nop 1
	v_add_f32_dpp v148, v148, v148 row_bcast:31 row_mask:0xc bank_mask:0xf
	s_nop 0
	v_readlane_b32 s0, v148, 63
	s_nop 1
	v_mov_b32_e32 v148, s0
	v_fmamk_f32 v148, v148, 0x3b000000, v162
	v_mul_f32_e32 v150, 0x4b800000, v148
	v_cmp_gt_f32_e32 vcc, s31, v148
	s_nop 1
	v_cndmask_b32_e32 v148, v148, v150, vcc
	v_rsq_f32_e32 v148, v148
	s_nop 0
	v_mul_f32_e32 v150, 0x45800000, v148
	v_cndmask_b32_e32 v149, v148, v150, vcc
	v_mul_f32_e32 v140, v149, v140
	v_mul_f32_e32 v141, v149, v141
	v_mul_f32_e32 v142, v149, v142
	v_mul_f32_e32 v143, v149, v143
	v_mul_f32_e32 v144, v149, v144
	v_mul_f32_e32 v145, v149, v145
	v_mul_f32_e32 v146, v149, v146
	v_mul_f32_e32 v147, v149, v147
	v_cvt_pk_bf16_f32 v140, v140, v141
	v_cvt_pk_bf16_f32 v141, v142, v143
	v_cvt_pk_bf16_f32 v142, v144, v145
	v_cvt_pk_bf16_f32 v143, v146, v147
	global_store_dwordx4 v[156:157], v[140:143], off offset:2048 sc1
	v_lshl_add_u64 v[156:157], v[156:157], 0, s[20:21]
	s_waitcnt vmcnt(10)
; __device__ __forceinline__ unsigned cvt_pk_bf16(float lo, float hi) { unsigned r; asm volatile("v_cvt_pk_bf16_f32 %0, %1, %2" : "=v"(r) : "v"(lo), "v"(hi)); return r; }
; __device__ __forceinline__ float bf_lo(unsigned w) { return __uint_as_float(w << 16); }
; __device__ __forceinline__ float bf_hi(unsigned w) { return __uint_as_float(w & 0xffff0000u); }
; __global__ void __launch_bounds__(512, 2) trunk_fwd(Args args) {
;     ...
;                 for (int rr = 0; rr < 16; ++rr) {
;                     const int r = r0 + rr;
;                     const u32x4 gb = gb_n, gu = gu_n; const f32x4 pv4 = pv_n;
;                     if (rr < 15) { gb_n = *(const u32x4*)(Z + (size_t)(r + 1) * INP + 768 + c0); gu_n = *(const u32x4*)(Z + (size_t)(r + 1) * INP + 1280 + c0);
;                                    pv_n = *(const f32x4*)(pl + (size_t)(r + 1) * PLE + lane * 4); }
;                     float cv[8], uu[8]; float ss = 0.f;
; #pragma unroll
;                     for (int i = 0; i < 4; ++i) {
;                         uu[2 * i] = bf_lo(gu[i]); uu[2 * i + 1] = bf_hi(gu[i]);
;                         cv[2 * i] = bf_lo(gb[i]) * (w0[2 * i] * uu[2 * i] + w1[2 * i] * u1[2 * i] + w2[2 * i] * u2[2 * i]);
;                         cv[2 * i + 1] = bf_hi(gb[i]) * (w0[2 * i + 1] * uu[2 * i + 1] + w1[2 * i + 1] * u1[2 * i + 1] + w2[2 * i + 1] * u2[2 * i + 1]);
;                     }
; #pragma unroll
;                     for (int i = 0; i < 8; ++i) { ss += cv[i] * cv[i]; u2[i] = u1[i]; u1[i] = uu[i]; }
;                     ss = wave_sum(ss);
;                     const float rc = rsqrtf(ss * (1.0f / 512.0f) + EPS);
;                     u32x4 oc;
; #pragma unroll
;                     for (int i = 0; i < 4; ++i) oc[i] = cvt_pk_bf16(cv[2 * i] * rc, cv[2 * i + 1] * rc);
;                     *(u32x4*)(MIX + (size_t)r * 1024 + 512 + c0) = oc;
;                     u32x2 pw; pw.x = cvt_pk_bf16(pv4[0], pv4[1]); pw.y = cvt_pk_bf16(pv4[2], pv4[3]);
;                     *(u32x2*)(PB + (size_t)r * PLE + lane * 4) = pw;
;                 }
	v_lshlrev_b32_e32 v204, 16, v68
	v_and_b32_e32 v205, 0xffff0000, v68
	v_lshlrev_b32_e32 v206, 16, v69
	v_and_b32_e32 v207, 0xffff0000, v69
	v_lshlrev_b32_e32 v208, 16, v70
	v_and_b32_e32 v209, 0xffff0000, v70
	v_lshlrev_b32_e32 v210, 16, v71
	v_and_b32_e32 v211, 0xffff0000, v71
	v_mul_f32_e32 v140, v164, v204
	v_mul_f32_e32 v141, v165, v205
	v_mul_f32_e32 v142, v166, v206
	v_mul_f32_e32 v143, v167, v207
	v_mul_f32_e32 v144, v168, v208
	v_mul_f32_e32 v145, v169, v209
	v_mul_f32_e32 v146, v170, v210
	v_mul_f32_e32 v147, v171, v211
	v_fmac_f32_e32 v140, v172, v196
	v_fmac_f32_e32 v141, v173, v197
	v_fmac_f32_e32 v142, v174, v198
	v_fmac_f32_e32 v143, v175, v199
	v_fmac_f32_e32 v144, v176, v200
	v_fmac_f32_e32 v145, v177, v201
	v_fmac_f32_e32 v146, v178, v202
	v_fmac_f32_e32 v147, v179, v203
	v_fmac_f32_e32 v140, v180, v188
	v_fmac_f32_e32 v141, v181, v189
	v_fmac_f32_e32 v142, v182, v190
	v_fmac_f32_e32 v143, v183, v191
	v_fmac_f32_e32 v144, v184, v192
	v_fmac_f32_e32 v145, v185, v193
	v_fmac_f32_e32 v146, v186, v194
	v_fmac_f32_e32 v147, v187, v195
	v_lshlrev_b32_e32 v150, 16, v42
	v_and_b32_e32 v151, 0xffff0000, v42
	v_mul_f32_e32 v140, v150, v140
	v_mul_f32_e32 v141, v151, v141
	v_lshlrev_b32_e32 v150, 16, v43
	v_and_b32_e32 v151, 0xffff0000, v43
	v_mul_f32_e32 v142, v150, v142
	v_mul_f32_e32 v143, v151, v143
	v_lshlrev_b32_e32 v150, 16, v44
	v_and_b32_e32 v151, 0xffff0000, v44
	v_mul_f32_e32 v144, v150, v144
	v_mul_f32_e32 v145, v151, v145
	v_lshlrev_b32_e32 v150, 16, v45
	v_and_b32_e32 v151, 0xffff0000, v45
	v_mul_f32_e32 v146, v150, v146
	v_mul_f32_e32 v147, v151, v147
	v_mul_f32_e32 v148, v140, v140
	v_fmac_f32_e32 v148, v141, v141
	v_fmac_f32_e32 v148, v142, v142
	v_fmac_f32_e32 v148, v143, v143
	v_fmac_f32_e32 v148, v144, v144
	v_fmac_f32_e32 v148, v145, v145
	v_fmac_f32_e32 v148, v146, v146
	v_fmac_f32_e32 v148, v147, v147
	s_nop 1
	v_add_f32_dpp v148, v148, v148 quad_perm:[1,0,3,2] row_mask:0xf bank_mask:0xf
	s_nop 1
	v_add_f32_dpp v148, v148, v148 quad_perm:[2,3,0,1] row_mask:0xf bank_mask:0xf
	s_nop 1
	v_add_f32_dpp v148, v148, v148 row_half_mirror row_mask:0xf bank_mask:0xf
	s_nop 1
	v_add_f32_dpp v148, v148, v148 row_mirror row_mask:0xf bank_mask:0xf
	s_nop 1
	v_add_f32_dpp v148, v148, v148 row_bcast:15 row_mask:0xa bank_mask:0xf
	s_nop 1
	v_add_f32_dpp v148, v148, v148 row_bcast:31 row_mask:0xc bank_mask:0xf
	s_nop 0
	v_readlane_b32 s0, v148, 63
	s_nop 1
	v_mov_b32_e32 v148, s0
	v_fmamk_f32 v148, v148, 0x3b000000, v162
	v_mul_f32_e32 v150, 0x4b800000, v148
	v_cmp_gt_f32_e32 vcc, s31, v148
	s_nop 1
	v_cndmask_b32_e32 v148, v148, v150, vcc
	v_rsq_f32_e32 v148, v148
	s_nop 0
	v_mul_f32_e32 v150, 0x45800000, v148
	v_cndmask_b32_e32 v149, v148, v150, vcc
	v_mul_f32_e32 v140, v149, v140
	v_mul_f32_e32 v141, v149, v141
	v_mul_f32_e32 v142, v149, v142
	v_mul_f32_e32 v143, v149, v143
	v_mul_f32_e32 v144, v149, v144
	v_mul_f32_e32 v145, v149, v145
	v_mul_f32_e32 v146, v149, v146
	v_mul_f32_e32 v147, v149, v147
	v_cvt_pk_bf16_f32 v140, v140, v141
	v_cvt_pk_bf16_f32 v141, v142, v143
	v_cvt_pk_bf16_f32 v142, v144, v145
	v_cvt_pk_bf16_f32 v143, v146, v147
	global_store_dwordx4 v[156:157], v[140:143], off sc1
	s_waitcnt vmcnt(8)
	v_lshlrev_b32_e32 v188, 16, v72
	v_and_b32_e32 v189, 0xffff0000, v72
	v_lshlrev_b32_e32 v190, 16, v73
	v_and_b32_e32 v191, 0xffff0000, v73
	v_lshlrev_b32_e32 v192, 16, v74
	v_and_b32_e32 v193, 0xffff0000, v74
	v_lshlrev_b32_e32 v194, 16, v75
	v_and_b32_e32 v195, 0xffff0000, v75
	v_mul_f32_e32 v140, v164, v188
	v_mul_f32_e32 v141, v165, v189
	v_mul_f32_e32 v142, v166, v190
	v_mul_f32_e32 v143, v167, v191
	v_mul_f32_e32 v144, v168, v192
	v_mul_f32_e32 v145, v169, v193
	v_mul_f32_e32 v146, v170, v194
	v_mul_f32_e32 v147, v171, v195
	v_fmac_f32_e32 v140, v172, v204
	v_fmac_f32_e32 v141, v173, v205
	v_fmac_f32_e32 v142, v174, v206
	v_fmac_f32_e32 v143, v175, v207
	v_fmac_f32_e32 v144, v176, v208
	v_fmac_f32_e32 v145, v177, v209
	v_fmac_f32_e32 v146, v178, v210
	v_fmac_f32_e32 v147, v179, v211
	v_fmac_f32_e32 v140, v180, v196
	v_fmac_f32_e32 v141, v181, v197
	v_fmac_f32_e32 v142, v182, v198
	v_fmac_f32_e32 v143, v183, v199
	v_fmac_f32_e32 v144, v184, v200
	v_fmac_f32_e32 v145, v185, v201
	v_fmac_f32_e32 v146, v186, v202
	v_fmac_f32_e32 v147, v187, v203
	v_lshlrev_b32_e32 v150, 16, v46
	v_and_b32_e32 v151, 0xffff0000, v46
	v_mul_f32_e32 v140, v150, v140
	v_mul_f32_e32 v141, v151, v141
	v_lshlrev_b32_e32 v150, 16, v47
	v_and_b32_e32 v151, 0xffff0000, v47
	v_mul_f32_e32 v142, v150, v142
	v_mul_f32_e32 v143, v151, v143
	v_lshlrev_b32_e32 v150, 16, v48
	v_and_b32_e32 v151, 0xffff0000, v48
	v_mul_f32_e32 v144, v150, v144
	v_mul_f32_e32 v145, v151, v145
	v_lshlrev_b32_e32 v150, 16, v49
	v_and_b32_e32 v151, 0xffff0000, v49
	v_mul_f32_e32 v146, v150, v146
	v_mul_f32_e32 v147, v151, v147
	v_mul_f32_e32 v148, v140, v140
	v_fmac_f32_e32 v148, v141, v141
	v_fmac_f32_e32 v148, v142, v142
	v_fmac_f32_e32 v148, v143, v143
	v_fmac_f32_e32 v148, v144, v144
	v_fmac_f32_e32 v148, v145, v145
	v_fmac_f32_e32 v148, v146, v146
	v_fmac_f32_e32 v148, v147, v147
	s_nop 1
	v_add_f32_dpp v148, v148, v148 quad_perm:[1,0,3,2] row_mask:0xf bank_mask:0xf
	s_nop 1
	v_add_f32_dpp v148, v148, v148 quad_perm:[2,3,0,1] row_mask:0xf bank_mask:0xf
	s_nop 1
	v_add_f32_dpp v148, v148, v148 row_half_mirror row_mask:0xf bank_mask:0xf
	s_nop 1
	v_add_f32_dpp v148, v148, v148 row_mirror row_mask:0xf bank_mask:0xf
	s_nop 1
	v_add_f32_dpp v148, v148, v148 row_bcast:15 row_mask:0xa bank_mask:0xf
	s_nop 1
	v_add_f32_dpp v148, v148, v148 row_bcast:31 row_mask:0xc bank_mask:0xf
	s_nop 0
	v_readlane_b32 s0, v148, 63
	s_nop 1
	v_mov_b32_e32 v148, s0
	v_fmamk_f32 v148, v148, 0x3b000000, v162
	v_mul_f32_e32 v150, 0x4b800000, v148
	v_cmp_gt_f32_e32 vcc, s31, v148
	s_nop 1
	v_cndmask_b32_e32 v148, v148, v150, vcc
	v_rsq_f32_e32 v148, v148
	s_nop 0
	v_mul_f32_e32 v150, 0x45800000, v148
	v_cndmask_b32_e32 v149, v148, v150, vcc
	v_mul_f32_e32 v140, v149, v140
	v_mul_f32_e32 v141, v149, v141
	v_mul_f32_e32 v142, v149, v142
	v_mul_f32_e32 v143, v149, v143
	v_mul_f32_e32 v144, v149, v144
	v_mul_f32_e32 v145, v149, v145
	v_mul_f32_e32 v146, v149, v146
	v_mul_f32_e32 v147, v149, v147
	v_cvt_pk_bf16_f32 v140, v140, v141
	v_cvt_pk_bf16_f32 v141, v142, v143
	v_cvt_pk_bf16_f32 v142, v144, v145
	v_cvt_pk_bf16_f32 v143, v146, v147
	global_store_dwordx4 v[156:157], v[140:143], off offset:2048 sc1
	v_lshl_add_u64 v[156:157], v[156:157], 0, s[20:21]
	s_branch .LBB0_1053
